# conv_unit GLU load stage rewritten: position rows requested together, single wait
# speedup vs baseline: 1.0436x; 1.0020x over previous
.LBB0_44:
	s_waitcnt vmcnt(0)
	v_mov_b32_e32 v8, v197
	s_nop 0
	v_and_b32_e32 v1, 63, v8
	v_ashrrev_i32_e32 v3, 6, v8
	v_lshlrev_b32_e32 v20, 3, v1
	v_cmp_gt_i32_e32 vcc, 62, v3
	s_barrier
	s_and_saveexec_b64 s[4:5], vcc
	s_cbranch_execz .LBB0_69
	s_add_i32 s29, s7, -15
	v_readfirstlane_b32 s26, v3
	v_lshlrev_b32_e32 v9, 4, v1
	v_lshl_add_u32 v11, v3, 10, v9
	s_nop 1
	s_add_i32 s29, s29, s26
	s_mov_b32 s30, s29
	v_mov_b32_e32 v24, 0
	v_mov_b32_e32 v25, 0
	v_mov_b32_e32 v26, 0
	v_mov_b32_e32 v27, 0
	s_cmp_ge_u32 s29, s28
	s_cbranch_scc1 .Lcv_skip0
	s_mul_i32 s27, s29, s25
	s_add_i32 s27, s27, s6
	s_mul_i32 s27, s27, 0x2800
	v_add_u32_e32 v10, s27, v9
	global_load_dwordx4 v[24:27], v10, s[20:21]
	global_load_dwordx4 v[28:31], v10, s[20:21] offset:1024
.Lcv_skip0:
	s_add_i32 s29, s29, 8
	v_mov_b32_e32 v32, 0
	v_mov_b32_e32 v33, 0
	v_mov_b32_e32 v34, 0
	v_mov_b32_e32 v35, 0
	s_cmp_ge_u32 s29, s28
	s_cbranch_scc1 .Lcv_skip1
	s_mul_i32 s27, s29, s25
	s_add_i32 s27, s27, s6
	s_mul_i32 s27, s27, 0x2800
	v_add_u32_e32 v10, s27, v9
	global_load_dwordx4 v[32:35], v10, s[20:21]
	global_load_dwordx4 v[36:39], v10, s[20:21] offset:1024
.Lcv_skip1:
	s_add_i32 s29, s29, 8
	v_mov_b32_e32 v40, 0
	v_mov_b32_e32 v41, 0
	v_mov_b32_e32 v42, 0
	v_mov_b32_e32 v43, 0
	s_cmp_ge_u32 s29, s28
	s_cbranch_scc1 .Lcv_skip2
	s_mul_i32 s27, s29, s25
	s_add_i32 s27, s27, s6
	s_mul_i32 s27, s27, 0x2800
	v_add_u32_e32 v10, s27, v9
	global_load_dwordx4 v[40:43], v10, s[20:21]
	global_load_dwordx4 v[44:47], v10, s[20:21] offset:1024
.Lcv_skip2:
	s_add_i32 s29, s29, 8
	v_mov_b32_e32 v48, 0
	v_mov_b32_e32 v49, 0
	v_mov_b32_e32 v50, 0
	v_mov_b32_e32 v51, 0
	s_cmp_ge_u32 s29, s28
	s_cbranch_scc1 .Lcv_skip3
	s_mul_i32 s27, s29, s25
	s_add_i32 s27, s27, s6
	s_mul_i32 s27, s27, 0x2800
	v_add_u32_e32 v10, s27, v9
	global_load_dwordx4 v[48:51], v10, s[20:21]
	global_load_dwordx4 v[52:55], v10, s[20:21] offset:1024
.Lcv_skip3:
	s_add_i32 s29, s29, 8
	v_mov_b32_e32 v56, 0
	v_mov_b32_e32 v57, 0
	v_mov_b32_e32 v58, 0
	v_mov_b32_e32 v59, 0
	s_cmp_ge_u32 s29, s28
	s_cbranch_scc1 .Lcv_skip4
	s_mul_i32 s27, s29, s25
	s_add_i32 s27, s27, s6
	s_mul_i32 s27, s27, 0x2800
	v_add_u32_e32 v10, s27, v9
	global_load_dwordx4 v[56:59], v10, s[20:21]
	global_load_dwordx4 v[60:63], v10, s[20:21] offset:1024
.Lcv_skip4:
	s_add_i32 s29, s29, 8
	v_mov_b32_e32 v64, 0
	v_mov_b32_e32 v65, 0
	v_mov_b32_e32 v66, 0
	v_mov_b32_e32 v67, 0
	s_cmp_ge_u32 s29, s28
	s_cbranch_scc1 .Lcv_skip5
	s_mul_i32 s27, s29, s25
	s_add_i32 s27, s27, s6
	s_mul_i32 s27, s27, 0x2800
	v_add_u32_e32 v10, s27, v9
	global_load_dwordx4 v[64:67], v10, s[20:21]
	global_load_dwordx4 v[68:71], v10, s[20:21] offset:1024
.Lcv_skip5:
	s_add_i32 s29, s29, 8
	v_mov_b32_e32 v72, 0
	v_mov_b32_e32 v73, 0
	v_mov_b32_e32 v74, 0
	v_mov_b32_e32 v75, 0
	s_cmp_ge_u32 s29, s28
	s_cbranch_scc1 .Lcv_skip6
	s_mul_i32 s27, s29, s25
	s_add_i32 s27, s27, s6
	s_mul_i32 s27, s27, 0x2800
	v_add_u32_e32 v10, s27, v9
	global_load_dwordx4 v[72:75], v10, s[20:21]
	global_load_dwordx4 v[76:79], v10, s[20:21] offset:1024
.Lcv_skip6:
	s_add_i32 s29, s29, 8
	s_cmp_ge_u32 s26, 6
	s_cbranch_scc1 .Lcv_issued
	v_mov_b32_e32 v80, 0
	v_mov_b32_e32 v81, 0
	v_mov_b32_e32 v82, 0
	v_mov_b32_e32 v83, 0
	s_cmp_ge_u32 s29, s28
	s_cbranch_scc1 .Lcv_skip7
	s_mul_i32 s27, s29, s25
	s_add_i32 s27, s27, s6
	s_mul_i32 s27, s27, 0x2800
	v_add_u32_e32 v10, s27, v9
	global_load_dwordx4 v[80:83], v10, s[20:21]
	global_load_dwordx4 v[84:87], v10, s[20:21] offset:1024
.Lcv_skip7:
	s_add_i32 s29, s29, 8
.Lcv_issued:
	s_waitcnt vmcnt(0)
	s_mov_b32 s29, s30
	s_cmp_ge_u32 s29, s28
	s_cbranch_scc1 .Lcv_w0
	v_cvt_f32_f16_e32 v4, v28
	v_cvt_f32_f16_sdwa v6, v28 dst_sel:DWORD dst_unused:UNUSED_PAD src0_sel:WORD_1
	v_cvt_f32_f16_e32 v12, v29
	v_cvt_f32_f16_sdwa v14, v29 dst_sel:DWORD dst_unused:UNUSED_PAD src0_sel:WORD_1
	v_cvt_f32_f16_e32 v5, v24
	v_cvt_f32_f16_sdwa v7, v24 dst_sel:DWORD dst_unused:UNUSED_PAD src0_sel:WORD_1
	v_cvt_f32_f16_e32 v13, v25
	v_cvt_f32_f16_sdwa v15, v25 dst_sel:DWORD dst_unused:UNUSED_PAD src0_sel:WORD_1
	v_mul_f32_e32 v4, 0xbfb8aa3b, v4
	v_mul_f32_e32 v6, 0xbfb8aa3b, v6
	v_mul_f32_e32 v12, 0xbfb8aa3b, v12
	v_mul_f32_e32 v14, 0xbfb8aa3b, v14
	v_exp_f32_e32 v4, v4
	v_exp_f32_e32 v6, v6
	v_exp_f32_e32 v12, v12
	v_exp_f32_e32 v14, v14
	v_add_f32_e32 v4, 1.0, v4
	v_add_f32_e32 v6, 1.0, v6
	v_add_f32_e32 v12, 1.0, v12
	v_add_f32_e32 v14, 1.0, v14
	v_rcp_f32_e32 v4, v4
	v_rcp_f32_e32 v6, v6
	v_rcp_f32_e32 v12, v12
	v_rcp_f32_e32 v14, v14
	v_mul_f32_e32 v4, v4, v5
	v_mul_f32_e32 v6, v6, v7
	v_mul_f32_e32 v12, v12, v13
	v_mul_f32_e32 v14, v14, v15
	v_cvt_pk_f16_f32 v24, v4, v6
	v_cvt_pk_f16_f32 v25, v12, v14
	v_cvt_f32_f16_e32 v4, v30
	v_cvt_f32_f16_sdwa v6, v30 dst_sel:DWORD dst_unused:UNUSED_PAD src0_sel:WORD_1
	v_cvt_f32_f16_e32 v12, v31
	v_cvt_f32_f16_sdwa v14, v31 dst_sel:DWORD dst_unused:UNUSED_PAD src0_sel:WORD_1
	v_cvt_f32_f16_e32 v5, v26
	v_cvt_f32_f16_sdwa v7, v26 dst_sel:DWORD dst_unused:UNUSED_PAD src0_sel:WORD_1
	v_cvt_f32_f16_e32 v13, v27
	v_cvt_f32_f16_sdwa v15, v27 dst_sel:DWORD dst_unused:UNUSED_PAD src0_sel:WORD_1
	v_mul_f32_e32 v4, 0xbfb8aa3b, v4
	v_mul_f32_e32 v6, 0xbfb8aa3b, v6
	v_mul_f32_e32 v12, 0xbfb8aa3b, v12
	v_mul_f32_e32 v14, 0xbfb8aa3b, v14
	v_exp_f32_e32 v4, v4
	v_exp_f32_e32 v6, v6
	v_exp_f32_e32 v12, v12
	v_exp_f32_e32 v14, v14
	v_add_f32_e32 v4, 1.0, v4
	v_add_f32_e32 v6, 1.0, v6
	v_add_f32_e32 v12, 1.0, v12
	v_add_f32_e32 v14, 1.0, v14
	v_rcp_f32_e32 v4, v4
	v_rcp_f32_e32 v6, v6
	v_rcp_f32_e32 v12, v12
	v_rcp_f32_e32 v14, v14
	v_mul_f32_e32 v4, v4, v5
	v_mul_f32_e32 v6, v6, v7
	v_mul_f32_e32 v12, v12, v13
	v_mul_f32_e32 v14, v14, v15
	v_cvt_pk_f16_f32 v26, v4, v6
	v_cvt_pk_f16_f32 v27, v12, v14
.Lcv_w0:
	ds_write_b128 v11, v[24:27] offset:0
	s_add_i32 s29, s29, 8
	s_cmp_ge_u32 s29, s28
	s_cbranch_scc1 .Lcv_w1
	v_cvt_f32_f16_e32 v4, v36
	v_cvt_f32_f16_sdwa v6, v36 dst_sel:DWORD dst_unused:UNUSED_PAD src0_sel:WORD_1
	v_cvt_f32_f16_e32 v12, v37
	v_cvt_f32_f16_sdwa v14, v37 dst_sel:DWORD dst_unused:UNUSED_PAD src0_sel:WORD_1
	v_cvt_f32_f16_e32 v5, v32
	v_cvt_f32_f16_sdwa v7, v32 dst_sel:DWORD dst_unused:UNUSED_PAD src0_sel:WORD_1
	v_cvt_f32_f16_e32 v13, v33
	v_cvt_f32_f16_sdwa v15, v33 dst_sel:DWORD dst_unused:UNUSED_PAD src0_sel:WORD_1
	v_mul_f32_e32 v4, 0xbfb8aa3b, v4
	v_mul_f32_e32 v6, 0xbfb8aa3b, v6
	v_mul_f32_e32 v12, 0xbfb8aa3b, v12
	v_mul_f32_e32 v14, 0xbfb8aa3b, v14
	v_exp_f32_e32 v4, v4
	v_exp_f32_e32 v6, v6
	v_exp_f32_e32 v12, v12
	v_exp_f32_e32 v14, v14
	v_add_f32_e32 v4, 1.0, v4
	v_add_f32_e32 v6, 1.0, v6
	v_add_f32_e32 v12, 1.0, v12
	v_add_f32_e32 v14, 1.0, v14
	v_rcp_f32_e32 v4, v4
	v_rcp_f32_e32 v6, v6
	v_rcp_f32_e32 v12, v12
	v_rcp_f32_e32 v14, v14
	v_mul_f32_e32 v4, v4, v5
	v_mul_f32_e32 v6, v6, v7
	v_mul_f32_e32 v12, v12, v13
	v_mul_f32_e32 v14, v14, v15
	v_cvt_pk_f16_f32 v32, v4, v6
	v_cvt_pk_f16_f32 v33, v12, v14
	v_cvt_f32_f16_e32 v4, v38
	v_cvt_f32_f16_sdwa v6, v38 dst_sel:DWORD dst_unused:UNUSED_PAD src0_sel:WORD_1
	v_cvt_f32_f16_e32 v12, v39
	v_cvt_f32_f16_sdwa v14, v39 dst_sel:DWORD dst_unused:UNUSED_PAD src0_sel:WORD_1
	v_cvt_f32_f16_e32 v5, v34
	v_cvt_f32_f16_sdwa v7, v34 dst_sel:DWORD dst_unused:UNUSED_PAD src0_sel:WORD_1
	v_cvt_f32_f16_e32 v13, v35
	v_cvt_f32_f16_sdwa v15, v35 dst_sel:DWORD dst_unused:UNUSED_PAD src0_sel:WORD_1
	v_mul_f32_e32 v4, 0xbfb8aa3b, v4
	v_mul_f32_e32 v6, 0xbfb8aa3b, v6
	v_mul_f32_e32 v12, 0xbfb8aa3b, v12
	v_mul_f32_e32 v14, 0xbfb8aa3b, v14
	v_exp_f32_e32 v4, v4
	v_exp_f32_e32 v6, v6
	v_exp_f32_e32 v12, v12
	v_exp_f32_e32 v14, v14
	v_add_f32_e32 v4, 1.0, v4
	v_add_f32_e32 v6, 1.0, v6
	v_add_f32_e32 v12, 1.0, v12
	v_add_f32_e32 v14, 1.0, v14
	v_rcp_f32_e32 v4, v4
	v_rcp_f32_e32 v6, v6
	v_rcp_f32_e32 v12, v12
	v_rcp_f32_e32 v14, v14
	v_mul_f32_e32 v4, v4, v5
	v_mul_f32_e32 v6, v6, v7
	v_mul_f32_e32 v12, v12, v13
	v_mul_f32_e32 v14, v14, v15
	v_cvt_pk_f16_f32 v34, v4, v6
	v_cvt_pk_f16_f32 v35, v12, v14
.Lcv_w1:
	ds_write_b128 v11, v[32:35] offset:8192
	s_add_i32 s29, s29, 8
	s_cmp_ge_u32 s29, s28
	s_cbranch_scc1 .Lcv_w2
	v_cvt_f32_f16_e32 v4, v44
	v_cvt_f32_f16_sdwa v6, v44 dst_sel:DWORD dst_unused:UNUSED_PAD src0_sel:WORD_1
	v_cvt_f32_f16_e32 v12, v45
	v_cvt_f32_f16_sdwa v14, v45 dst_sel:DWORD dst_unused:UNUSED_PAD src0_sel:WORD_1
	v_cvt_f32_f16_e32 v5, v40
	v_cvt_f32_f16_sdwa v7, v40 dst_sel:DWORD dst_unused:UNUSED_PAD src0_sel:WORD_1
	v_cvt_f32_f16_e32 v13, v41
	v_cvt_f32_f16_sdwa v15, v41 dst_sel:DWORD dst_unused:UNUSED_PAD src0_sel:WORD_1
	v_mul_f32_e32 v4, 0xbfb8aa3b, v4
	v_mul_f32_e32 v6, 0xbfb8aa3b, v6
	v_mul_f32_e32 v12, 0xbfb8aa3b, v12
	v_mul_f32_e32 v14, 0xbfb8aa3b, v14
	v_exp_f32_e32 v4, v4
	v_exp_f32_e32 v6, v6
	v_exp_f32_e32 v12, v12
	v_exp_f32_e32 v14, v14
	v_add_f32_e32 v4, 1.0, v4
	v_add_f32_e32 v6, 1.0, v6
	v_add_f32_e32 v12, 1.0, v12
	v_add_f32_e32 v14, 1.0, v14
	v_rcp_f32_e32 v4, v4
	v_rcp_f32_e32 v6, v6
	v_rcp_f32_e32 v12, v12
	v_rcp_f32_e32 v14, v14
	v_mul_f32_e32 v4, v4, v5
	v_mul_f32_e32 v6, v6, v7
	v_mul_f32_e32 v12, v12, v13
	v_mul_f32_e32 v14, v14, v15
	v_cvt_pk_f16_f32 v40, v4, v6
	v_cvt_pk_f16_f32 v41, v12, v14
	v_cvt_f32_f16_e32 v4, v46
	v_cvt_f32_f16_sdwa v6, v46 dst_sel:DWORD dst_unused:UNUSED_PAD src0_sel:WORD_1
	v_cvt_f32_f16_e32 v12, v47
	v_cvt_f32_f16_sdwa v14, v47 dst_sel:DWORD dst_unused:UNUSED_PAD src0_sel:WORD_1
	v_cvt_f32_f16_e32 v5, v42
	v_cvt_f32_f16_sdwa v7, v42 dst_sel:DWORD dst_unused:UNUSED_PAD src0_sel:WORD_1
	v_cvt_f32_f16_e32 v13, v43
	v_cvt_f32_f16_sdwa v15, v43 dst_sel:DWORD dst_unused:UNUSED_PAD src0_sel:WORD_1
	v_mul_f32_e32 v4, 0xbfb8aa3b, v4
	v_mul_f32_e32 v6, 0xbfb8aa3b, v6
	v_mul_f32_e32 v12, 0xbfb8aa3b, v12
	v_mul_f32_e32 v14, 0xbfb8aa3b, v14
	v_exp_f32_e32 v4, v4
	v_exp_f32_e32 v6, v6
	v_exp_f32_e32 v12, v12
	v_exp_f32_e32 v14, v14
	v_add_f32_e32 v4, 1.0, v4
	v_add_f32_e32 v6, 1.0, v6
	v_add_f32_e32 v12, 1.0, v12
	v_add_f32_e32 v14, 1.0, v14
	v_rcp_f32_e32 v4, v4
	v_rcp_f32_e32 v6, v6
	v_rcp_f32_e32 v12, v12
	v_rcp_f32_e32 v14, v14
	v_mul_f32_e32 v4, v4, v5
	v_mul_f32_e32 v6, v6, v7
	v_mul_f32_e32 v12, v12, v13
	v_mul_f32_e32 v14, v14, v15
	v_cvt_pk_f16_f32 v42, v4, v6
	v_cvt_pk_f16_f32 v43, v12, v14
.Lcv_w2:
	ds_write_b128 v11, v[40:43] offset:16384
	s_add_i32 s29, s29, 8
	s_cmp_ge_u32 s29, s28
	s_cbranch_scc1 .Lcv_w3
	v_cvt_f32_f16_e32 v4, v52
	v_cvt_f32_f16_sdwa v6, v52 dst_sel:DWORD dst_unused:UNUSED_PAD src0_sel:WORD_1
	v_cvt_f32_f16_e32 v12, v53
	v_cvt_f32_f16_sdwa v14, v53 dst_sel:DWORD dst_unused:UNUSED_PAD src0_sel:WORD_1
	v_cvt_f32_f16_e32 v5, v48
	v_cvt_f32_f16_sdwa v7, v48 dst_sel:DWORD dst_unused:UNUSED_PAD src0_sel:WORD_1
	v_cvt_f32_f16_e32 v13, v49
	v_cvt_f32_f16_sdwa v15, v49 dst_sel:DWORD dst_unused:UNUSED_PAD src0_sel:WORD_1
	v_mul_f32_e32 v4, 0xbfb8aa3b, v4
	v_mul_f32_e32 v6, 0xbfb8aa3b, v6
	v_mul_f32_e32 v12, 0xbfb8aa3b, v12
	v_mul_f32_e32 v14, 0xbfb8aa3b, v14
	v_exp_f32_e32 v4, v4
	v_exp_f32_e32 v6, v6
	v_exp_f32_e32 v12, v12
	v_exp_f32_e32 v14, v14
	v_add_f32_e32 v4, 1.0, v4
	v_add_f32_e32 v6, 1.0, v6
	v_add_f32_e32 v12, 1.0, v12
	v_add_f32_e32 v14, 1.0, v14
	v_rcp_f32_e32 v4, v4
	v_rcp_f32_e32 v6, v6
	v_rcp_f32_e32 v12, v12
	v_rcp_f32_e32 v14, v14
	v_mul_f32_e32 v4, v4, v5
	v_mul_f32_e32 v6, v6, v7
	v_mul_f32_e32 v12, v12, v13
	v_mul_f32_e32 v14, v14, v15
	v_cvt_pk_f16_f32 v48, v4, v6
	v_cvt_pk_f16_f32 v49, v12, v14
	v_cvt_f32_f16_e32 v4, v54
	v_cvt_f32_f16_sdwa v6, v54 dst_sel:DWORD dst_unused:UNUSED_PAD src0_sel:WORD_1
	v_cvt_f32_f16_e32 v12, v55
	v_cvt_f32_f16_sdwa v14, v55 dst_sel:DWORD dst_unused:UNUSED_PAD src0_sel:WORD_1
	v_cvt_f32_f16_e32 v5, v50
	v_cvt_f32_f16_sdwa v7, v50 dst_sel:DWORD dst_unused:UNUSED_PAD src0_sel:WORD_1
	v_cvt_f32_f16_e32 v13, v51
	v_cvt_f32_f16_sdwa v15, v51 dst_sel:DWORD dst_unused:UNUSED_PAD src0_sel:WORD_1
	v_mul_f32_e32 v4, 0xbfb8aa3b, v4
	v_mul_f32_e32 v6, 0xbfb8aa3b, v6
	v_mul_f32_e32 v12, 0xbfb8aa3b, v12
	v_mul_f32_e32 v14, 0xbfb8aa3b, v14
	v_exp_f32_e32 v4, v4
	v_exp_f32_e32 v6, v6
	v_exp_f32_e32 v12, v12
	v_exp_f32_e32 v14, v14
	v_add_f32_e32 v4, 1.0, v4
	v_add_f32_e32 v6, 1.0, v6
	v_add_f32_e32 v12, 1.0, v12
	v_add_f32_e32 v14, 1.0, v14
	v_rcp_f32_e32 v4, v4
	v_rcp_f32_e32 v6, v6
	v_rcp_f32_e32 v12, v12
	v_rcp_f32_e32 v14, v14
	v_mul_f32_e32 v4, v4, v5
	v_mul_f32_e32 v6, v6, v7
	v_mul_f32_e32 v12, v12, v13
	v_mul_f32_e32 v14, v14, v15
	v_cvt_pk_f16_f32 v50, v4, v6
	v_cvt_pk_f16_f32 v51, v12, v14
.Lcv_w3:
	ds_write_b128 v11, v[48:51] offset:24576
	s_add_i32 s29, s29, 8
	s_cmp_ge_u32 s29, s28
	s_cbranch_scc1 .Lcv_w4
	v_cvt_f32_f16_e32 v4, v60
	v_cvt_f32_f16_sdwa v6, v60 dst_sel:DWORD dst_unused:UNUSED_PAD src0_sel:WORD_1
	v_cvt_f32_f16_e32 v12, v61
	v_cvt_f32_f16_sdwa v14, v61 dst_sel:DWORD dst_unused:UNUSED_PAD src0_sel:WORD_1
	v_cvt_f32_f16_e32 v5, v56
	v_cvt_f32_f16_sdwa v7, v56 dst_sel:DWORD dst_unused:UNUSED_PAD src0_sel:WORD_1
	v_cvt_f32_f16_e32 v13, v57
	v_cvt_f32_f16_sdwa v15, v57 dst_sel:DWORD dst_unused:UNUSED_PAD src0_sel:WORD_1
	v_mul_f32_e32 v4, 0xbfb8aa3b, v4
	v_mul_f32_e32 v6, 0xbfb8aa3b, v6
	v_mul_f32_e32 v12, 0xbfb8aa3b, v12
	v_mul_f32_e32 v14, 0xbfb8aa3b, v14
	v_exp_f32_e32 v4, v4
	v_exp_f32_e32 v6, v6
	v_exp_f32_e32 v12, v12
	v_exp_f32_e32 v14, v14
	v_add_f32_e32 v4, 1.0, v4
	v_add_f32_e32 v6, 1.0, v6
	v_add_f32_e32 v12, 1.0, v12
	v_add_f32_e32 v14, 1.0, v14
	v_rcp_f32_e32 v4, v4
	v_rcp_f32_e32 v6, v6
	v_rcp_f32_e32 v12, v12
	v_rcp_f32_e32 v14, v14
	v_mul_f32_e32 v4, v4, v5
	v_mul_f32_e32 v6, v6, v7
	v_mul_f32_e32 v12, v12, v13
	v_mul_f32_e32 v14, v14, v15
	v_cvt_pk_f16_f32 v56, v4, v6
	v_cvt_pk_f16_f32 v57, v12, v14
	v_cvt_f32_f16_e32 v4, v62
	v_cvt_f32_f16_sdwa v6, v62 dst_sel:DWORD dst_unused:UNUSED_PAD src0_sel:WORD_1
	v_cvt_f32_f16_e32 v12, v63
	v_cvt_f32_f16_sdwa v14, v63 dst_sel:DWORD dst_unused:UNUSED_PAD src0_sel:WORD_1
	v_cvt_f32_f16_e32 v5, v58
	v_cvt_f32_f16_sdwa v7, v58 dst_sel:DWORD dst_unused:UNUSED_PAD src0_sel:WORD_1
	v_cvt_f32_f16_e32 v13, v59
	v_cvt_f32_f16_sdwa v15, v59 dst_sel:DWORD dst_unused:UNUSED_PAD src0_sel:WORD_1
	v_mul_f32_e32 v4, 0xbfb8aa3b, v4
	v_mul_f32_e32 v6, 0xbfb8aa3b, v6
	v_mul_f32_e32 v12, 0xbfb8aa3b, v12
	v_mul_f32_e32 v14, 0xbfb8aa3b, v14
	v_exp_f32_e32 v4, v4
	v_exp_f32_e32 v6, v6
	v_exp_f32_e32 v12, v12
	v_exp_f32_e32 v14, v14
	v_add_f32_e32 v4, 1.0, v4
	v_add_f32_e32 v6, 1.0, v6
	v_add_f32_e32 v12, 1.0, v12
	v_add_f32_e32 v14, 1.0, v14
	v_rcp_f32_e32 v4, v4
	v_rcp_f32_e32 v6, v6
	v_rcp_f32_e32 v12, v12
	v_rcp_f32_e32 v14, v14
	v_mul_f32_e32 v4, v4, v5
	v_mul_f32_e32 v6, v6, v7
	v_mul_f32_e32 v12, v12, v13
	v_mul_f32_e32 v14, v14, v15
	v_cvt_pk_f16_f32 v58, v4, v6
	v_cvt_pk_f16_f32 v59, v12, v14
.Lcv_w4:
	ds_write_b128 v11, v[56:59] offset:32768
	s_add_i32 s29, s29, 8
	s_cmp_ge_u32 s29, s28
	s_cbranch_scc1 .Lcv_w5
	v_cvt_f32_f16_e32 v4, v68
	v_cvt_f32_f16_sdwa v6, v68 dst_sel:DWORD dst_unused:UNUSED_PAD src0_sel:WORD_1
	v_cvt_f32_f16_e32 v12, v69
	v_cvt_f32_f16_sdwa v14, v69 dst_sel:DWORD dst_unused:UNUSED_PAD src0_sel:WORD_1
	v_cvt_f32_f16_e32 v5, v64
	v_cvt_f32_f16_sdwa v7, v64 dst_sel:DWORD dst_unused:UNUSED_PAD src0_sel:WORD_1
	v_cvt_f32_f16_e32 v13, v65
	v_cvt_f32_f16_sdwa v15, v65 dst_sel:DWORD dst_unused:UNUSED_PAD src0_sel:WORD_1
	v_mul_f32_e32 v4, 0xbfb8aa3b, v4
	v_mul_f32_e32 v6, 0xbfb8aa3b, v6
	v_mul_f32_e32 v12, 0xbfb8aa3b, v12
	v_mul_f32_e32 v14, 0xbfb8aa3b, v14
	v_exp_f32_e32 v4, v4
	v_exp_f32_e32 v6, v6
	v_exp_f32_e32 v12, v12
	v_exp_f32_e32 v14, v14
	v_add_f32_e32 v4, 1.0, v4
	v_add_f32_e32 v6, 1.0, v6
	v_add_f32_e32 v12, 1.0, v12
	v_add_f32_e32 v14, 1.0, v14
	v_rcp_f32_e32 v4, v4
	v_rcp_f32_e32 v6, v6
	v_rcp_f32_e32 v12, v12
	v_rcp_f32_e32 v14, v14
	v_mul_f32_e32 v4, v4, v5
	v_mul_f32_e32 v6, v6, v7
	v_mul_f32_e32 v12, v12, v13
	v_mul_f32_e32 v14, v14, v15
	v_cvt_pk_f16_f32 v64, v4, v6
	v_cvt_pk_f16_f32 v65, v12, v14
	v_cvt_f32_f16_e32 v4, v70
	v_cvt_f32_f16_sdwa v6, v70 dst_sel:DWORD dst_unused:UNUSED_PAD src0_sel:WORD_1
	v_cvt_f32_f16_e32 v12, v71
	v_cvt_f32_f16_sdwa v14, v71 dst_sel:DWORD dst_unused:UNUSED_PAD src0_sel:WORD_1
	v_cvt_f32_f16_e32 v5, v66
	v_cvt_f32_f16_sdwa v7, v66 dst_sel:DWORD dst_unused:UNUSED_PAD src0_sel:WORD_1
	v_cvt_f32_f16_e32 v13, v67
	v_cvt_f32_f16_sdwa v15, v67 dst_sel:DWORD dst_unused:UNUSED_PAD src0_sel:WORD_1
	v_mul_f32_e32 v4, 0xbfb8aa3b, v4
	v_mul_f32_e32 v6, 0xbfb8aa3b, v6
	v_mul_f32_e32 v12, 0xbfb8aa3b, v12
	v_mul_f32_e32 v14, 0xbfb8aa3b, v14
	v_exp_f32_e32 v4, v4
	v_exp_f32_e32 v6, v6
	v_exp_f32_e32 v12, v12
	v_exp_f32_e32 v14, v14
	v_add_f32_e32 v4, 1.0, v4
	v_add_f32_e32 v6, 1.0, v6
	v_add_f32_e32 v12, 1.0, v12
	v_add_f32_e32 v14, 1.0, v14
	v_rcp_f32_e32 v4, v4
	v_rcp_f32_e32 v6, v6
	v_rcp_f32_e32 v12, v12
	v_rcp_f32_e32 v14, v14
	v_mul_f32_e32 v4, v4, v5
	v_mul_f32_e32 v6, v6, v7
	v_mul_f32_e32 v12, v12, v13
	v_mul_f32_e32 v14, v14, v15
	v_cvt_pk_f16_f32 v66, v4, v6
	v_cvt_pk_f16_f32 v67, v12, v14
.Lcv_w5:
	ds_write_b128 v11, v[64:67] offset:40960
	s_add_i32 s29, s29, 8
	s_cmp_ge_u32 s29, s28
	s_cbranch_scc1 .Lcv_w6
	v_cvt_f32_f16_e32 v4, v76
	v_cvt_f32_f16_sdwa v6, v76 dst_sel:DWORD dst_unused:UNUSED_PAD src0_sel:WORD_1
	v_cvt_f32_f16_e32 v12, v77
	v_cvt_f32_f16_sdwa v14, v77 dst_sel:DWORD dst_unused:UNUSED_PAD src0_sel:WORD_1
	v_cvt_f32_f16_e32 v5, v72
	v_cvt_f32_f16_sdwa v7, v72 dst_sel:DWORD dst_unused:UNUSED_PAD src0_sel:WORD_1
	v_cvt_f32_f16_e32 v13, v73
	v_cvt_f32_f16_sdwa v15, v73 dst_sel:DWORD dst_unused:UNUSED_PAD src0_sel:WORD_1
	v_mul_f32_e32 v4, 0xbfb8aa3b, v4
	v_mul_f32_e32 v6, 0xbfb8aa3b, v6
	v_mul_f32_e32 v12, 0xbfb8aa3b, v12
	v_mul_f32_e32 v14, 0xbfb8aa3b, v14
	v_exp_f32_e32 v4, v4
	v_exp_f32_e32 v6, v6
	v_exp_f32_e32 v12, v12
	v_exp_f32_e32 v14, v14
	v_add_f32_e32 v4, 1.0, v4
	v_add_f32_e32 v6, 1.0, v6
	v_add_f32_e32 v12, 1.0, v12
	v_add_f32_e32 v14, 1.0, v14
	v_rcp_f32_e32 v4, v4
	v_rcp_f32_e32 v6, v6
	v_rcp_f32_e32 v12, v12
	v_rcp_f32_e32 v14, v14
	v_mul_f32_e32 v4, v4, v5
	v_mul_f32_e32 v6, v6, v7
	v_mul_f32_e32 v12, v12, v13
	v_mul_f32_e32 v14, v14, v15
	v_cvt_pk_f16_f32 v72, v4, v6
	v_cvt_pk_f16_f32 v73, v12, v14
	v_cvt_f32_f16_e32 v4, v78
	v_cvt_f32_f16_sdwa v6, v78 dst_sel:DWORD dst_unused:UNUSED_PAD src0_sel:WORD_1
	v_cvt_f32_f16_e32 v12, v79
	v_cvt_f32_f16_sdwa v14, v79 dst_sel:DWORD dst_unused:UNUSED_PAD src0_sel:WORD_1
	v_cvt_f32_f16_e32 v5, v74
	v_cvt_f32_f16_sdwa v7, v74 dst_sel:DWORD dst_unused:UNUSED_PAD src0_sel:WORD_1
	v_cvt_f32_f16_e32 v13, v75
	v_cvt_f32_f16_sdwa v15, v75 dst_sel:DWORD dst_unused:UNUSED_PAD src0_sel:WORD_1
	v_mul_f32_e32 v4, 0xbfb8aa3b, v4
	v_mul_f32_e32 v6, 0xbfb8aa3b, v6
	v_mul_f32_e32 v12, 0xbfb8aa3b, v12
	v_mul_f32_e32 v14, 0xbfb8aa3b, v14
	v_exp_f32_e32 v4, v4
	v_exp_f32_e32 v6, v6
	v_exp_f32_e32 v12, v12
	v_exp_f32_e32 v14, v14
	v_add_f32_e32 v4, 1.0, v4
	v_add_f32_e32 v6, 1.0, v6
	v_add_f32_e32 v12, 1.0, v12
	v_add_f32_e32 v14, 1.0, v14
	v_rcp_f32_e32 v4, v4
	v_rcp_f32_e32 v6, v6
	v_rcp_f32_e32 v12, v12
	v_rcp_f32_e32 v14, v14
	v_mul_f32_e32 v4, v4, v5
	v_mul_f32_e32 v6, v6, v7
	v_mul_f32_e32 v12, v12, v13
	v_mul_f32_e32 v14, v14, v15
	v_cvt_pk_f16_f32 v74, v4, v6
	v_cvt_pk_f16_f32 v75, v12, v14
.Lcv_w6:
	ds_write_b128 v11, v[72:75] offset:49152
	s_add_i32 s29, s29, 8
	s_cmp_ge_u32 s26, 6
	s_cbranch_scc1 .Lcv_done
	s_cmp_ge_u32 s29, s28
	s_cbranch_scc1 .Lcv_w7
	v_cvt_f32_f16_e32 v4, v84
	v_cvt_f32_f16_sdwa v6, v84 dst_sel:DWORD dst_unused:UNUSED_PAD src0_sel:WORD_1
	v_cvt_f32_f16_e32 v12, v85
	v_cvt_f32_f16_sdwa v14, v85 dst_sel:DWORD dst_unused:UNUSED_PAD src0_sel:WORD_1
	v_cvt_f32_f16_e32 v5, v80
	v_cvt_f32_f16_sdwa v7, v80 dst_sel:DWORD dst_unused:UNUSED_PAD src0_sel:WORD_1
	v_cvt_f32_f16_e32 v13, v81
	v_cvt_f32_f16_sdwa v15, v81 dst_sel:DWORD dst_unused:UNUSED_PAD src0_sel:WORD_1
	v_mul_f32_e32 v4, 0xbfb8aa3b, v4
	v_mul_f32_e32 v6, 0xbfb8aa3b, v6
	v_mul_f32_e32 v12, 0xbfb8aa3b, v12
	v_mul_f32_e32 v14, 0xbfb8aa3b, v14
	v_exp_f32_e32 v4, v4
	v_exp_f32_e32 v6, v6
	v_exp_f32_e32 v12, v12
	v_exp_f32_e32 v14, v14
	v_add_f32_e32 v4, 1.0, v4
	v_add_f32_e32 v6, 1.0, v6
	v_add_f32_e32 v12, 1.0, v12
	v_add_f32_e32 v14, 1.0, v14
	v_rcp_f32_e32 v4, v4
	v_rcp_f32_e32 v6, v6
	v_rcp_f32_e32 v12, v12
	v_rcp_f32_e32 v14, v14
	v_mul_f32_e32 v4, v4, v5
	v_mul_f32_e32 v6, v6, v7
	v_mul_f32_e32 v12, v12, v13
	v_mul_f32_e32 v14, v14, v15
	v_cvt_pk_f16_f32 v80, v4, v6
	v_cvt_pk_f16_f32 v81, v12, v14
	v_cvt_f32_f16_e32 v4, v86
	v_cvt_f32_f16_sdwa v6, v86 dst_sel:DWORD dst_unused:UNUSED_PAD src0_sel:WORD_1
	v_cvt_f32_f16_e32 v12, v87
	v_cvt_f32_f16_sdwa v14, v87 dst_sel:DWORD dst_unused:UNUSED_PAD src0_sel:WORD_1
	v_cvt_f32_f16_e32 v5, v82
	v_cvt_f32_f16_sdwa v7, v82 dst_sel:DWORD dst_unused:UNUSED_PAD src0_sel:WORD_1
	v_cvt_f32_f16_e32 v13, v83
	v_cvt_f32_f16_sdwa v15, v83 dst_sel:DWORD dst_unused:UNUSED_PAD src0_sel:WORD_1
	v_mul_f32_e32 v4, 0xbfb8aa3b, v4
	v_mul_f32_e32 v6, 0xbfb8aa3b, v6
	v_mul_f32_e32 v12, 0xbfb8aa3b, v12
	v_mul_f32_e32 v14, 0xbfb8aa3b, v14
	v_exp_f32_e32 v4, v4
	v_exp_f32_e32 v6, v6
	v_exp_f32_e32 v12, v12
	v_exp_f32_e32 v14, v14
	v_add_f32_e32 v4, 1.0, v4
	v_add_f32_e32 v6, 1.0, v6
	v_add_f32_e32 v12, 1.0, v12
	v_add_f32_e32 v14, 1.0, v14
	v_rcp_f32_e32 v4, v4
	v_rcp_f32_e32 v6, v6
	v_rcp_f32_e32 v12, v12
	v_rcp_f32_e32 v14, v14
	v_mul_f32_e32 v4, v4, v5
	v_mul_f32_e32 v6, v6, v7
	v_mul_f32_e32 v12, v12, v13
	v_mul_f32_e32 v14, v14, v15
	v_cvt_pk_f16_f32 v82, v4, v6
	v_cvt_pk_f16_f32 v83, v12, v14
.Lcv_w7:
	ds_write_b128 v11, v[80:83] offset:57344
	s_add_i32 s29, s29, 8
.Lcv_done:
.LBB0_69:
	s_or_b64 exec, exec, s[4:5]
	v_ashrrev_i32_e32 v9, 31, v8
	v_lshl_add_u64 v[36:37], v[8:9], 2, s[8:9]
	v_add_co_u32_e32 v10, vcc, 0x1000, v36
	s_waitcnt lgkmcnt(0)
	s_nop 0
	v_addc_co_u32_e32 v11, vcc, 0, v37, vcc
	s_barrier
	global_load_dword v4, v[36:37], off
	global_load_dword v5, v[36:37], off offset:2048
	global_load_dword v6, v[10:11], off
	global_load_dword v7, v[10:11], off offset:2048
	v_add_co_u32_e32 v10, vcc, 0x2000, v36
	v_lshl_add_u32 v68, v8, 1, 0
	s_nop 0
	v_addc_co_u32_e32 v11, vcc, 0, v37, vcc
	v_add_co_u32_e32 v12, vcc, 0x3000, v36
	global_load_dword v9, v[10:11], off
	s_nop 0
	global_load_dword v10, v[10:11], off offset:2048
	v_addc_co_u32_e32 v13, vcc, 0, v37, vcc
	v_add_co_u32_e32 v14, vcc, 0x4000, v36
	global_load_dword v11, v[12:13], off
	s_nop 0
	global_load_dword v12, v[12:13], off offset:2048
	v_addc_co_u32_e32 v15, vcc, 0, v37, vcc
	v_add_co_u32_e32 v16, vcc, 0x5000, v36
	global_load_dword v13, v[14:15], off
	s_nop 0
	global_load_dword v14, v[14:15], off offset:2048
	v_addc_co_u32_e32 v17, vcc, 0, v37, vcc
	v_add_co_u32_e32 v18, vcc, 0x6000, v36
	global_load_dword v15, v[16:17], off
	s_nop 0
	global_load_dword v16, v[16:17], off offset:2048
	v_addc_co_u32_e32 v19, vcc, 0, v37, vcc
	v_add_co_u32_e32 v22, vcc, 0x7000, v36
	global_load_dword v17, v[18:19], off
	s_nop 0
	global_load_dword v18, v[18:19], off offset:2048
	v_addc_co_u32_e32 v23, vcc, 0, v37, vcc
	v_add_co_u32_e32 v24, vcc, 0x8000, v36
	global_load_dword v19, v[22:23], off
	global_load_dword v21, v[22:23], off offset:2048
	v_addc_co_u32_e32 v25, vcc, 0, v37, vcc
	v_add_co_u32_e32 v26, vcc, 0x9000, v36
	global_load_dword v22, v[24:25], off
	global_load_dword v23, v[24:25], off offset:2048
	v_addc_co_u32_e32 v27, vcc, 0, v37, vcc
	v_add_co_u32_e32 v28, vcc, 0xa000, v36
	global_load_dword v24, v[26:27], off
	global_load_dword v25, v[26:27], off offset:2048
	v_addc_co_u32_e32 v29, vcc, 0, v37, vcc
	v_add_co_u32_e32 v30, vcc, 0xb000, v36
	global_load_dword v26, v[28:29], off
	global_load_dword v27, v[28:29], off offset:2048
	v_addc_co_u32_e32 v31, vcc, 0, v37, vcc
	v_add_co_u32_e32 v32, vcc, 0xc000, v36
	global_load_dword v28, v[30:31], off
	global_load_dword v29, v[30:31], off offset:2048
	v_addc_co_u32_e32 v33, vcc, 0, v37, vcc
	v_add_co_u32_e32 v34, vcc, 0xd000, v36
	global_load_dword v30, v[32:33], off
	global_load_dword v31, v[32:33], off offset:2048
	v_addc_co_u32_e32 v35, vcc, 0, v37, vcc
	v_add_co_u32_e32 v38, vcc, 0xe000, v36
	global_load_dword v32, v[34:35], off
	global_load_dword v33, v[34:35], off offset:2048
	v_addc_co_u32_e32 v39, vcc, 0, v37, vcc
	global_load_dword v34, v[38:39], off
	global_load_dword v35, v[38:39], off offset:2048
	v_add_u32_e32 v38, s24, v8
	v_add_co_u32_e32 v36, vcc, 0xf000, v36
	v_ashrrev_i32_e32 v39, 31, v38
	s_nop 0
	v_addc_co_u32_e32 v37, vcc, 0, v37, vcc
	v_lshl_add_u64 v[38:39], v[38:39], 2, s[10:11]
	global_load_dword v36, v[36:37], off
	v_lshl_add_u32 v100, v8, 2, 0
	global_load_dword v37, v[38:39], off
	ds_read_u16 v85, v68
	ds_read_u16 v86, v68 offset:1024
	ds_read_u16 v87, v68 offset:2048
	ds_read_u16 v88, v68 offset:3072
	ds_read_u16 v89, v68 offset:4096
	ds_read_u16 v90, v68 offset:5120
	ds_read_u16 v91, v68 offset:6144
	ds_read_u16 v92, v68 offset:7168
	ds_read_u16 v93, v68 offset:8192
	ds_read_u16 v94, v68 offset:9216
	ds_read_u16 v95, v68 offset:10240
	ds_read_u16 v96, v68 offset:11264
	ds_read_u16 v97, v68 offset:12288
	ds_read_u16 v98, v68 offset:13312
	ds_read_u16 v99, v68 offset:14336
	ds_read_u16 v84, v68 offset:15360
	ds_read_u16 v83, v68 offset:16384
	ds_read_u16 v82, v68 offset:17408
	ds_read_u16 v81, v68 offset:18432
	ds_read_u16 v80, v68 offset:19456
	ds_read_u16 v79, v68 offset:20480
	ds_read_u16 v78, v68 offset:21504
	ds_read_u16 v77, v68 offset:22528
	ds_read_u16 v76, v68 offset:23552
	ds_read_u16 v75, v68 offset:24576
	ds_read_u16 v74, v68 offset:25600
	ds_read_u16 v73, v68 offset:26624
	ds_read_u16 v72, v68 offset:27648
	ds_read_u16 v71, v68 offset:28672
	ds_read_u16 v70, v68 offset:29696
	ds_read_u16 v69, v68 offset:30720
	ds_read_u16 v38, v68 offset:31744
	ds_read_u16 v39, v68 offset:32768
	ds_read_u16 v40, v68 offset:33792
	ds_read_u16 v41, v68 offset:34816
	ds_read_u16 v42, v68 offset:35840
	ds_read_u16 v43, v68 offset:36864
	ds_read_u16 v44, v68 offset:37888
	ds_read_u16 v45, v68 offset:38912
	ds_read_u16 v46, v68 offset:39936
	ds_read_u16 v47, v68 offset:40960
	ds_read_u16 v48, v68 offset:41984
	ds_read_u16 v49, v68 offset:43008
	ds_read_u16 v50, v68 offset:44032
	ds_read_u16 v51, v68 offset:45056
	ds_read_u16 v52, v68 offset:46080
	ds_read_u16 v53, v68 offset:47104
	ds_read_u16 v54, v68 offset:48128
	ds_read_u16 v55, v68 offset:49152
	ds_read_u16 v56, v68 offset:50176
	ds_read_u16 v57, v68 offset:51200
	ds_read_u16 v58, v68 offset:52224
	ds_read_u16 v59, v68 offset:53248
	ds_read_u16 v60, v68 offset:54272
	ds_read_u16 v61, v68 offset:55296
	ds_read_u16 v62, v68 offset:56320
	ds_read_u16 v63, v68 offset:57344
	ds_read_u16 v64, v68 offset:58368
	ds_read_u16 v65, v68 offset:59392
	ds_read_u16 v66, v68 offset:60416
	ds_read_u16 v67, v68 offset:61440
	ds_read_u16 v68, v68 offset:62464
	v_add_u32_e32 v8, 0xf800, v100
	v_cmp_gt_i32_e32 vcc, 32, v3
	s_waitcnt vmcnt(0) lgkmcnt(14)
	v_fma_mix_f32 v85, v4, v85, v37 op_sel_hi:[0,1,0]
	v_fma_mix_f32 v85, v5, v86, v85 op_sel_hi:[0,1,0]
	v_fma_mix_f32 v85, v6, v87, v85 op_sel_hi:[0,1,0]
	v_fma_mix_f32 v85, v7, v88, v85 op_sel_hi:[0,1,0]
	v_fma_mix_f32 v85, v9, v89, v85 op_sel_hi:[0,1,0]
	v_fma_mix_f32 v85, v10, v90, v85 op_sel_hi:[0,1,0]
	v_fma_mix_f32 v85, v11, v91, v85 op_sel_hi:[0,1,0]
	v_fma_mix_f32 v85, v12, v92, v85 op_sel_hi:[0,1,0]
	v_fma_mix_f32 v85, v13, v93, v85 op_sel_hi:[0,1,0]
	v_fma_mix_f32 v85, v14, v94, v85 op_sel_hi:[0,1,0]
	v_fma_mix_f32 v85, v15, v95, v85 op_sel_hi:[0,1,0]
	v_fma_mix_f32 v85, v16, v96, v85 op_sel_hi:[0,1,0]
	v_fma_mix_f32 v85, v17, v97, v85 op_sel_hi:[0,1,0]
	v_fma_mix_f32 v85, v18, v98, v85 op_sel_hi:[0,1,0]
	v_fma_mix_f32 v85, v19, v99, v85 op_sel_hi:[0,1,0]
	v_fma_mix_f32 v85, v21, v84, v85 op_sel_hi:[0,1,0]
	v_fma_mix_f32 v85, v22, v83, v85 op_sel_hi:[0,1,0]
	v_fma_mix_f32 v85, v23, v82, v85 op_sel_hi:[0,1,0]
	v_fma_mix_f32 v85, v24, v81, v85 op_sel_hi:[0,1,0]
	v_fma_mix_f32 v85, v25, v80, v85 op_sel_hi:[0,1,0]
	v_fma_mix_f32 v85, v26, v79, v85 op_sel_hi:[0,1,0]
	v_fma_mix_f32 v85, v27, v78, v85 op_sel_hi:[0,1,0]
	v_fma_mix_f32 v85, v28, v77, v85 op_sel_hi:[0,1,0]
	v_fma_mix_f32 v85, v29, v76, v85 op_sel_hi:[0,1,0]
	v_fma_mix_f32 v85, v30, v75, v85 op_sel_hi:[0,1,0]
	v_fma_mix_f32 v85, v31, v74, v85 op_sel_hi:[0,1,0]
	v_fma_mix_f32 v85, v32, v73, v85 op_sel_hi:[0,1,0]
	v_fma_mix_f32 v85, v33, v72, v85 op_sel_hi:[0,1,0]
	v_fma_mix_f32 v85, v34, v71, v85 op_sel_hi:[0,1,0]
	v_fma_mix_f32 v85, v35, v70, v85 op_sel_hi:[0,1,0]
	v_fma_mix_f32 v85, v36, v69, v85 op_sel_hi:[0,1,0]
	ds_write_b32 v100, v85 offset:63488
	v_fma_mix_f32 v85, v4, v86, v37 op_sel_hi:[0,1,0]
	v_fma_mix_f32 v86, v4, v87, v37 op_sel_hi:[0,1,0]
	v_fma_mix_f32 v85, v5, v87, v85 op_sel_hi:[0,1,0]
	v_fma_mix_f32 v86, v5, v88, v86 op_sel_hi:[0,1,0]
	v_fma_mix_f32 v85, v6, v88, v85 op_sel_hi:[0,1,0]
	v_fma_mix_f32 v86, v6, v89, v86 op_sel_hi:[0,1,0]
	v_fma_mix_f32 v85, v7, v89, v85 op_sel_hi:[0,1,0]
	v_fma_mix_f32 v86, v7, v90, v86 op_sel_hi:[0,1,0]
	v_fma_mix_f32 v85, v9, v90, v85 op_sel_hi:[0,1,0]
	v_fma_mix_f32 v86, v9, v91, v86 op_sel_hi:[0,1,0]
	v_fma_mix_f32 v85, v10, v91, v85 op_sel_hi:[0,1,0]
	v_fma_mix_f32 v86, v10, v92, v86 op_sel_hi:[0,1,0]
	v_fma_mix_f32 v85, v11, v92, v85 op_sel_hi:[0,1,0]
	v_fma_mix_f32 v86, v11, v93, v86 op_sel_hi:[0,1,0]
	v_fma_mix_f32 v85, v12, v93, v85 op_sel_hi:[0,1,0]
	v_fma_mix_f32 v86, v12, v94, v86 op_sel_hi:[0,1,0]
	v_fma_mix_f32 v85, v13, v94, v85 op_sel_hi:[0,1,0]
	v_fma_mix_f32 v86, v13, v95, v86 op_sel_hi:[0,1,0]
	v_fma_mix_f32 v85, v14, v95, v85 op_sel_hi:[0,1,0]
	v_fma_mix_f32 v86, v14, v96, v86 op_sel_hi:[0,1,0]
	v_fma_mix_f32 v85, v15, v96, v85 op_sel_hi:[0,1,0]
	v_fma_mix_f32 v86, v15, v97, v86 op_sel_hi:[0,1,0]
	v_fma_mix_f32 v85, v16, v97, v85 op_sel_hi:[0,1,0]
	v_fma_mix_f32 v86, v16, v98, v86 op_sel_hi:[0,1,0]
	v_fma_mix_f32 v85, v17, v98, v85 op_sel_hi:[0,1,0]
	v_fma_mix_f32 v86, v17, v99, v86 op_sel_hi:[0,1,0]
	v_fma_mix_f32 v85, v18, v99, v85 op_sel_hi:[0,1,0]
	v_fma_mix_f32 v86, v18, v84, v86 op_sel_hi:[0,1,0]
	v_fma_mix_f32 v85, v19, v84, v85 op_sel_hi:[0,1,0]
	v_fma_mix_f32 v86, v19, v83, v86 op_sel_hi:[0,1,0]
	v_fma_mix_f32 v85, v21, v83, v85 op_sel_hi:[0,1,0]
	v_fma_mix_f32 v86, v21, v82, v86 op_sel_hi:[0,1,0]
	v_fma_mix_f32 v85, v22, v82, v85 op_sel_hi:[0,1,0]
	v_fma_mix_f32 v86, v22, v81, v86 op_sel_hi:[0,1,0]
	v_fma_mix_f32 v85, v23, v81, v85 op_sel_hi:[0,1,0]
	v_fma_mix_f32 v86, v23, v80, v86 op_sel_hi:[0,1,0]
	v_fma_mix_f32 v85, v24, v80, v85 op_sel_hi:[0,1,0]
	v_fma_mix_f32 v86, v24, v79, v86 op_sel_hi:[0,1,0]
	v_fma_mix_f32 v85, v25, v79, v85 op_sel_hi:[0,1,0]
	v_fma_mix_f32 v86, v25, v78, v86 op_sel_hi:[0,1,0]
	v_fma_mix_f32 v85, v26, v78, v85 op_sel_hi:[0,1,0]
	v_fma_mix_f32 v86, v26, v77, v86 op_sel_hi:[0,1,0]
	v_fma_mix_f32 v85, v27, v77, v85 op_sel_hi:[0,1,0]
	v_fma_mix_f32 v86, v27, v76, v86 op_sel_hi:[0,1,0]
	v_fma_mix_f32 v85, v28, v76, v85 op_sel_hi:[0,1,0]
	v_fma_mix_f32 v86, v28, v75, v86 op_sel_hi:[0,1,0]
	v_fma_mix_f32 v85, v29, v75, v85 op_sel_hi:[0,1,0]
	v_fma_mix_f32 v86, v29, v74, v86 op_sel_hi:[0,1,0]
	v_fma_mix_f32 v85, v30, v74, v85 op_sel_hi:[0,1,0]
	v_fma_mix_f32 v86, v30, v73, v86 op_sel_hi:[0,1,0]
	v_fma_mix_f32 v85, v31, v73, v85 op_sel_hi:[0,1,0]
	v_fma_mix_f32 v86, v31, v72, v86 op_sel_hi:[0,1,0]
	v_fma_mix_f32 v85, v32, v72, v85 op_sel_hi:[0,1,0]
	v_fma_mix_f32 v86, v32, v71, v86 op_sel_hi:[0,1,0]
	v_fma_mix_f32 v85, v33, v71, v85 op_sel_hi:[0,1,0]
	v_fma_mix_f32 v86, v33, v70, v86 op_sel_hi:[0,1,0]
	v_fma_mix_f32 v85, v34, v70, v85 op_sel_hi:[0,1,0]
	v_fma_mix_f32 v86, v34, v69, v86 op_sel_hi:[0,1,0]
	v_fma_mix_f32 v85, v35, v69, v85 op_sel_hi:[0,1,0]
	v_fma_mix_f32 v86, v35, v38, v86 op_sel_hi:[0,1,0]
	v_fma_mix_f32 v85, v36, v38, v85 op_sel_hi:[0,1,0]
	v_fma_mix_f32 v86, v36, v39, v86 op_sel_hi:[0,1,0]
	ds_write2st64_b32 v8, v85, v86 offset0:8 offset1:16
	v_fma_mix_f32 v85, v4, v88, v37 op_sel_hi:[0,1,0]
	v_fma_mix_f32 v86, v4, v89, v37 op_sel_hi:[0,1,0]
	v_fma_mix_f32 v85, v5, v89, v85 op_sel_hi:[0,1,0]
	v_fma_mix_f32 v86, v5, v90, v86 op_sel_hi:[0,1,0]
	v_fma_mix_f32 v85, v6, v90, v85 op_sel_hi:[0,1,0]
	v_fma_mix_f32 v86, v6, v91, v86 op_sel_hi:[0,1,0]
	v_fma_mix_f32 v85, v7, v91, v85 op_sel_hi:[0,1,0]
	v_fma_mix_f32 v86, v7, v92, v86 op_sel_hi:[0,1,0]
	v_fma_mix_f32 v85, v9, v92, v85 op_sel_hi:[0,1,0]
	v_fma_mix_f32 v86, v9, v93, v86 op_sel_hi:[0,1,0]
	v_fma_mix_f32 v85, v10, v93, v85 op_sel_hi:[0,1,0]
	v_fma_mix_f32 v86, v10, v94, v86 op_sel_hi:[0,1,0]
	v_fma_mix_f32 v85, v11, v94, v85 op_sel_hi:[0,1,0]
	v_fma_mix_f32 v86, v11, v95, v86 op_sel_hi:[0,1,0]
	v_fma_mix_f32 v85, v12, v95, v85 op_sel_hi:[0,1,0]
	v_fma_mix_f32 v86, v12, v96, v86 op_sel_hi:[0,1,0]
	v_fma_mix_f32 v85, v13, v96, v85 op_sel_hi:[0,1,0]
	v_fma_mix_f32 v86, v13, v97, v86 op_sel_hi:[0,1,0]
	v_fma_mix_f32 v85, v14, v97, v85 op_sel_hi:[0,1,0]
	v_fma_mix_f32 v86, v14, v98, v86 op_sel_hi:[0,1,0]
	v_fma_mix_f32 v85, v15, v98, v85 op_sel_hi:[0,1,0]
	v_fma_mix_f32 v86, v15, v99, v86 op_sel_hi:[0,1,0]
	v_fma_mix_f32 v85, v16, v99, v85 op_sel_hi:[0,1,0]
	v_fma_mix_f32 v86, v16, v84, v86 op_sel_hi:[0,1,0]
	v_fma_mix_f32 v85, v17, v84, v85 op_sel_hi:[0,1,0]
	v_fma_mix_f32 v86, v17, v83, v86 op_sel_hi:[0,1,0]
	v_fma_mix_f32 v85, v18, v83, v85 op_sel_hi:[0,1,0]
	v_fma_mix_f32 v86, v18, v82, v86 op_sel_hi:[0,1,0]
	v_fma_mix_f32 v85, v19, v82, v85 op_sel_hi:[0,1,0]
	v_fma_mix_f32 v86, v19, v81, v86 op_sel_hi:[0,1,0]
	v_fma_mix_f32 v85, v21, v81, v85 op_sel_hi:[0,1,0]
	v_fma_mix_f32 v86, v21, v80, v86 op_sel_hi:[0,1,0]
	v_fma_mix_f32 v85, v22, v80, v85 op_sel_hi:[0,1,0]
	v_fma_mix_f32 v86, v22, v79, v86 op_sel_hi:[0,1,0]
	v_fma_mix_f32 v85, v23, v79, v85 op_sel_hi:[0,1,0]
	v_fma_mix_f32 v86, v23, v78, v86 op_sel_hi:[0,1,0]
	v_fma_mix_f32 v85, v24, v78, v85 op_sel_hi:[0,1,0]
	v_fma_mix_f32 v86, v24, v77, v86 op_sel_hi:[0,1,0]
	v_fma_mix_f32 v85, v25, v77, v85 op_sel_hi:[0,1,0]
	v_fma_mix_f32 v86, v25, v76, v86 op_sel_hi:[0,1,0]
	v_fma_mix_f32 v85, v26, v76, v85 op_sel_hi:[0,1,0]
	v_fma_mix_f32 v86, v26, v75, v86 op_sel_hi:[0,1,0]
	v_fma_mix_f32 v85, v27, v75, v85 op_sel_hi:[0,1,0]
	v_fma_mix_f32 v86, v27, v74, v86 op_sel_hi:[0,1,0]
	v_fma_mix_f32 v85, v28, v74, v85 op_sel_hi:[0,1,0]
	v_fma_mix_f32 v86, v28, v73, v86 op_sel_hi:[0,1,0]
	v_fma_mix_f32 v85, v29, v73, v85 op_sel_hi:[0,1,0]
	v_fma_mix_f32 v86, v29, v72, v86 op_sel_hi:[0,1,0]
	v_fma_mix_f32 v85, v30, v72, v85 op_sel_hi:[0,1,0]
	v_fma_mix_f32 v86, v30, v71, v86 op_sel_hi:[0,1,0]
	v_fma_mix_f32 v85, v31, v71, v85 op_sel_hi:[0,1,0]
	v_fma_mix_f32 v86, v31, v70, v86 op_sel_hi:[0,1,0]
	v_fma_mix_f32 v85, v32, v70, v85 op_sel_hi:[0,1,0]
	v_fma_mix_f32 v86, v32, v69, v86 op_sel_hi:[0,1,0]
	v_fma_mix_f32 v85, v33, v69, v85 op_sel_hi:[0,1,0]
	v_fma_mix_f32 v86, v33, v38, v86 op_sel_hi:[0,1,0]
	v_fma_mix_f32 v85, v34, v38, v85 op_sel_hi:[0,1,0]
	v_fma_mix_f32 v86, v34, v39, v86 op_sel_hi:[0,1,0]
	v_fma_mix_f32 v85, v35, v39, v85 op_sel_hi:[0,1,0]
	v_fma_mix_f32 v86, v35, v40, v86 op_sel_hi:[0,1,0]
	v_fma_mix_f32 v85, v36, v40, v85 op_sel_hi:[0,1,0]
	v_fma_mix_f32 v86, v36, v41, v86 op_sel_hi:[0,1,0]
	ds_write2st64_b32 v8, v85, v86 offset0:24 offset1:32
	v_fma_mix_f32 v85, v4, v90, v37 op_sel_hi:[0,1,0]
	v_fma_mix_f32 v86, v4, v91, v37 op_sel_hi:[0,1,0]
	v_fma_mix_f32 v85, v5, v91, v85 op_sel_hi:[0,1,0]
	v_fma_mix_f32 v86, v5, v92, v86 op_sel_hi:[0,1,0]
	v_fma_mix_f32 v85, v6, v92, v85 op_sel_hi:[0,1,0]
	v_fma_mix_f32 v86, v6, v93, v86 op_sel_hi:[0,1,0]
	v_fma_mix_f32 v85, v7, v93, v85 op_sel_hi:[0,1,0]
	v_fma_mix_f32 v86, v7, v94, v86 op_sel_hi:[0,1,0]
	v_fma_mix_f32 v85, v9, v94, v85 op_sel_hi:[0,1,0]
	v_fma_mix_f32 v86, v9, v95, v86 op_sel_hi:[0,1,0]
	v_fma_mix_f32 v85, v10, v95, v85 op_sel_hi:[0,1,0]
	v_fma_mix_f32 v86, v10, v96, v86 op_sel_hi:[0,1,0]
	v_fma_mix_f32 v85, v11, v96, v85 op_sel_hi:[0,1,0]
	v_fma_mix_f32 v86, v11, v97, v86 op_sel_hi:[0,1,0]
	v_fma_mix_f32 v85, v12, v97, v85 op_sel_hi:[0,1,0]
	v_fma_mix_f32 v86, v12, v98, v86 op_sel_hi:[0,1,0]
	v_fma_mix_f32 v85, v13, v98, v85 op_sel_hi:[0,1,0]
	v_fma_mix_f32 v86, v13, v99, v86 op_sel_hi:[0,1,0]
	v_fma_mix_f32 v85, v14, v99, v85 op_sel_hi:[0,1,0]
	v_fma_mix_f32 v86, v14, v84, v86 op_sel_hi:[0,1,0]
	v_fma_mix_f32 v85, v15, v84, v85 op_sel_hi:[0,1,0]
	v_fma_mix_f32 v86, v15, v83, v86 op_sel_hi:[0,1,0]
	v_fma_mix_f32 v85, v16, v83, v85 op_sel_hi:[0,1,0]
	v_fma_mix_f32 v86, v16, v82, v86 op_sel_hi:[0,1,0]
	v_fma_mix_f32 v85, v17, v82, v85 op_sel_hi:[0,1,0]
	v_fma_mix_f32 v86, v17, v81, v86 op_sel_hi:[0,1,0]
	v_fma_mix_f32 v85, v18, v81, v85 op_sel_hi:[0,1,0]
	v_fma_mix_f32 v86, v18, v80, v86 op_sel_hi:[0,1,0]
	v_fma_mix_f32 v85, v19, v80, v85 op_sel_hi:[0,1,0]
	v_fma_mix_f32 v86, v19, v79, v86 op_sel_hi:[0,1,0]
	v_fma_mix_f32 v85, v21, v79, v85 op_sel_hi:[0,1,0]
	v_fma_mix_f32 v86, v21, v78, v86 op_sel_hi:[0,1,0]
	v_fma_mix_f32 v85, v22, v78, v85 op_sel_hi:[0,1,0]
	v_fma_mix_f32 v86, v22, v77, v86 op_sel_hi:[0,1,0]
	v_fma_mix_f32 v85, v23, v77, v85 op_sel_hi:[0,1,0]
	v_fma_mix_f32 v86, v23, v76, v86 op_sel_hi:[0,1,0]
	v_fma_mix_f32 v85, v24, v76, v85 op_sel_hi:[0,1,0]
	v_fma_mix_f32 v86, v24, v75, v86 op_sel_hi:[0,1,0]
	v_fma_mix_f32 v85, v25, v75, v85 op_sel_hi:[0,1,0]
	v_fma_mix_f32 v86, v25, v74, v86 op_sel_hi:[0,1,0]
	v_fma_mix_f32 v85, v26, v74, v85 op_sel_hi:[0,1,0]
	v_fma_mix_f32 v86, v26, v73, v86 op_sel_hi:[0,1,0]
	v_fma_mix_f32 v85, v27, v73, v85 op_sel_hi:[0,1,0]
	v_fma_mix_f32 v86, v27, v72, v86 op_sel_hi:[0,1,0]
	v_fma_mix_f32 v85, v28, v72, v85 op_sel_hi:[0,1,0]
	v_fma_mix_f32 v86, v28, v71, v86 op_sel_hi:[0,1,0]
	v_fma_mix_f32 v85, v29, v71, v85 op_sel_hi:[0,1,0]
	v_fma_mix_f32 v86, v29, v70, v86 op_sel_hi:[0,1,0]
	v_fma_mix_f32 v85, v30, v70, v85 op_sel_hi:[0,1,0]
	v_fma_mix_f32 v86, v30, v69, v86 op_sel_hi:[0,1,0]
	v_fma_mix_f32 v85, v31, v69, v85 op_sel_hi:[0,1,0]
	v_fma_mix_f32 v86, v31, v38, v86 op_sel_hi:[0,1,0]
	v_fma_mix_f32 v85, v32, v38, v85 op_sel_hi:[0,1,0]
	v_fma_mix_f32 v86, v32, v39, v86 op_sel_hi:[0,1,0]
	v_fma_mix_f32 v85, v33, v39, v85 op_sel_hi:[0,1,0]
	v_fma_mix_f32 v86, v33, v40, v86 op_sel_hi:[0,1,0]
	v_fma_mix_f32 v85, v34, v40, v85 op_sel_hi:[0,1,0]
	v_fma_mix_f32 v86, v34, v41, v86 op_sel_hi:[0,1,0]
	v_fma_mix_f32 v85, v35, v41, v85 op_sel_hi:[0,1,0]
	v_fma_mix_f32 v86, v35, v42, v86 op_sel_hi:[0,1,0]
	v_fma_mix_f32 v85, v36, v42, v85 op_sel_hi:[0,1,0]
	v_fma_mix_f32 v86, v36, v43, v86 op_sel_hi:[0,1,0]
	ds_write2st64_b32 v8, v85, v86 offset0:40 offset1:48
	v_fma_mix_f32 v85, v4, v92, v37 op_sel_hi:[0,1,0]
	v_fma_mix_f32 v86, v4, v93, v37 op_sel_hi:[0,1,0]
	v_fma_mix_f32 v85, v5, v93, v85 op_sel_hi:[0,1,0]
	v_fma_mix_f32 v86, v5, v94, v86 op_sel_hi:[0,1,0]
	v_fma_mix_f32 v85, v6, v94, v85 op_sel_hi:[0,1,0]
	v_fma_mix_f32 v86, v6, v95, v86 op_sel_hi:[0,1,0]
	v_fma_mix_f32 v85, v7, v95, v85 op_sel_hi:[0,1,0]
	v_fma_mix_f32 v86, v7, v96, v86 op_sel_hi:[0,1,0]
	v_fma_mix_f32 v85, v9, v96, v85 op_sel_hi:[0,1,0]
	v_fma_mix_f32 v86, v9, v97, v86 op_sel_hi:[0,1,0]
	v_fma_mix_f32 v85, v10, v97, v85 op_sel_hi:[0,1,0]
	v_fma_mix_f32 v86, v10, v98, v86 op_sel_hi:[0,1,0]
	v_fma_mix_f32 v85, v11, v98, v85 op_sel_hi:[0,1,0]
	v_fma_mix_f32 v86, v11, v99, v86 op_sel_hi:[0,1,0]
	v_fma_mix_f32 v85, v12, v99, v85 op_sel_hi:[0,1,0]
	v_fma_mix_f32 v86, v12, v84, v86 op_sel_hi:[0,1,0]
	v_fma_mix_f32 v85, v13, v84, v85 op_sel_hi:[0,1,0]
	v_fma_mix_f32 v86, v13, v83, v86 op_sel_hi:[0,1,0]
	v_fma_mix_f32 v85, v14, v83, v85 op_sel_hi:[0,1,0]
	v_fma_mix_f32 v86, v14, v82, v86 op_sel_hi:[0,1,0]
	v_fma_mix_f32 v85, v15, v82, v85 op_sel_hi:[0,1,0]
	v_fma_mix_f32 v86, v15, v81, v86 op_sel_hi:[0,1,0]
	v_fma_mix_f32 v85, v16, v81, v85 op_sel_hi:[0,1,0]
	v_fma_mix_f32 v86, v16, v80, v86 op_sel_hi:[0,1,0]
	v_fma_mix_f32 v85, v17, v80, v85 op_sel_hi:[0,1,0]
	v_fma_mix_f32 v86, v17, v79, v86 op_sel_hi:[0,1,0]
	v_fma_mix_f32 v85, v18, v79, v85 op_sel_hi:[0,1,0]
	v_fma_mix_f32 v86, v18, v78, v86 op_sel_hi:[0,1,0]
	v_fma_mix_f32 v85, v19, v78, v85 op_sel_hi:[0,1,0]
	v_fma_mix_f32 v86, v19, v77, v86 op_sel_hi:[0,1,0]
	v_fma_mix_f32 v85, v21, v77, v85 op_sel_hi:[0,1,0]
	v_fma_mix_f32 v86, v21, v76, v86 op_sel_hi:[0,1,0]
	v_fma_mix_f32 v85, v22, v76, v85 op_sel_hi:[0,1,0]
	v_fma_mix_f32 v86, v22, v75, v86 op_sel_hi:[0,1,0]
	v_fma_mix_f32 v85, v23, v75, v85 op_sel_hi:[0,1,0]
	v_fma_mix_f32 v86, v23, v74, v86 op_sel_hi:[0,1,0]
	v_fma_mix_f32 v85, v24, v74, v85 op_sel_hi:[0,1,0]
	v_fma_mix_f32 v86, v24, v73, v86 op_sel_hi:[0,1,0]
	v_fma_mix_f32 v85, v25, v73, v85 op_sel_hi:[0,1,0]
	v_fma_mix_f32 v86, v25, v72, v86 op_sel_hi:[0,1,0]
	v_fma_mix_f32 v85, v26, v72, v85 op_sel_hi:[0,1,0]
	v_fma_mix_f32 v86, v26, v71, v86 op_sel_hi:[0,1,0]
	v_fma_mix_f32 v85, v27, v71, v85 op_sel_hi:[0,1,0]
	v_fma_mix_f32 v86, v27, v70, v86 op_sel_hi:[0,1,0]
	v_fma_mix_f32 v85, v28, v70, v85 op_sel_hi:[0,1,0]
	v_fma_mix_f32 v86, v28, v69, v86 op_sel_hi:[0,1,0]
	v_fma_mix_f32 v85, v29, v69, v85 op_sel_hi:[0,1,0]
	v_fma_mix_f32 v86, v29, v38, v86 op_sel_hi:[0,1,0]
	v_fma_mix_f32 v85, v30, v38, v85 op_sel_hi:[0,1,0]
	v_fma_mix_f32 v86, v30, v39, v86 op_sel_hi:[0,1,0]
	v_fma_mix_f32 v85, v31, v39, v85 op_sel_hi:[0,1,0]
	v_fma_mix_f32 v86, v31, v40, v86 op_sel_hi:[0,1,0]
	v_fma_mix_f32 v85, v32, v40, v85 op_sel_hi:[0,1,0]
	v_fma_mix_f32 v86, v32, v41, v86 op_sel_hi:[0,1,0]
	v_fma_mix_f32 v85, v33, v41, v85 op_sel_hi:[0,1,0]
	v_fma_mix_f32 v86, v33, v42, v86 op_sel_hi:[0,1,0]
	v_fma_mix_f32 v85, v34, v42, v85 op_sel_hi:[0,1,0]
	v_fma_mix_f32 v86, v34, v43, v86 op_sel_hi:[0,1,0]
	v_fma_mix_f32 v85, v35, v43, v85 op_sel_hi:[0,1,0]
	v_fma_mix_f32 v86, v35, v44, v86 op_sel_hi:[0,1,0]
	v_fma_mix_f32 v85, v36, v44, v85 op_sel_hi:[0,1,0]
	v_fma_mix_f32 v86, v36, v45, v86 op_sel_hi:[0,1,0]
	ds_write2st64_b32 v8, v85, v86 offset0:56 offset1:64
	v_fma_mix_f32 v85, v4, v94, v37 op_sel_hi:[0,1,0]
	v_fma_mix_f32 v86, v4, v95, v37 op_sel_hi:[0,1,0]
	v_fma_mix_f32 v85, v5, v95, v85 op_sel_hi:[0,1,0]
	v_fma_mix_f32 v86, v5, v96, v86 op_sel_hi:[0,1,0]
	v_fma_mix_f32 v85, v6, v96, v85 op_sel_hi:[0,1,0]
	v_fma_mix_f32 v86, v6, v97, v86 op_sel_hi:[0,1,0]
	v_fma_mix_f32 v85, v7, v97, v85 op_sel_hi:[0,1,0]
	v_fma_mix_f32 v86, v7, v98, v86 op_sel_hi:[0,1,0]
	v_fma_mix_f32 v85, v9, v98, v85 op_sel_hi:[0,1,0]
	v_fma_mix_f32 v86, v9, v99, v86 op_sel_hi:[0,1,0]
	v_fma_mix_f32 v85, v10, v99, v85 op_sel_hi:[0,1,0]
	v_fma_mix_f32 v86, v10, v84, v86 op_sel_hi:[0,1,0]
	v_fma_mix_f32 v85, v11, v84, v85 op_sel_hi:[0,1,0]
	v_fma_mix_f32 v86, v11, v83, v86 op_sel_hi:[0,1,0]
	v_fma_mix_f32 v85, v12, v83, v85 op_sel_hi:[0,1,0]
	v_fma_mix_f32 v86, v12, v82, v86 op_sel_hi:[0,1,0]
	v_fma_mix_f32 v85, v13, v82, v85 op_sel_hi:[0,1,0]
	v_fma_mix_f32 v86, v13, v81, v86 op_sel_hi:[0,1,0]
	v_fma_mix_f32 v85, v14, v81, v85 op_sel_hi:[0,1,0]
	v_fma_mix_f32 v86, v14, v80, v86 op_sel_hi:[0,1,0]
	v_fma_mix_f32 v85, v15, v80, v85 op_sel_hi:[0,1,0]
	v_fma_mix_f32 v86, v15, v79, v86 op_sel_hi:[0,1,0]
	v_fma_mix_f32 v85, v16, v79, v85 op_sel_hi:[0,1,0]
	v_fma_mix_f32 v86, v16, v78, v86 op_sel_hi:[0,1,0]
	v_fma_mix_f32 v85, v17, v78, v85 op_sel_hi:[0,1,0]
	v_fma_mix_f32 v86, v17, v77, v86 op_sel_hi:[0,1,0]
	v_fma_mix_f32 v85, v18, v77, v85 op_sel_hi:[0,1,0]
	v_fma_mix_f32 v86, v18, v76, v86 op_sel_hi:[0,1,0]
	v_fma_mix_f32 v85, v19, v76, v85 op_sel_hi:[0,1,0]
	v_fma_mix_f32 v86, v19, v75, v86 op_sel_hi:[0,1,0]
	v_fma_mix_f32 v85, v21, v75, v85 op_sel_hi:[0,1,0]
	v_fma_mix_f32 v86, v21, v74, v86 op_sel_hi:[0,1,0]
	v_fma_mix_f32 v85, v22, v74, v85 op_sel_hi:[0,1,0]
	v_fma_mix_f32 v86, v22, v73, v86 op_sel_hi:[0,1,0]
	v_fma_mix_f32 v85, v23, v73, v85 op_sel_hi:[0,1,0]
	v_fma_mix_f32 v86, v23, v72, v86 op_sel_hi:[0,1,0]
	v_fma_mix_f32 v85, v24, v72, v85 op_sel_hi:[0,1,0]
	v_fma_mix_f32 v86, v24, v71, v86 op_sel_hi:[0,1,0]
	v_fma_mix_f32 v85, v25, v71, v85 op_sel_hi:[0,1,0]
	v_fma_mix_f32 v86, v25, v70, v86 op_sel_hi:[0,1,0]
	v_fma_mix_f32 v85, v26, v70, v85 op_sel_hi:[0,1,0]
	v_fma_mix_f32 v86, v26, v69, v86 op_sel_hi:[0,1,0]
	v_fma_mix_f32 v85, v27, v69, v85 op_sel_hi:[0,1,0]
	v_fma_mix_f32 v86, v27, v38, v86 op_sel_hi:[0,1,0]
	v_fma_mix_f32 v85, v28, v38, v85 op_sel_hi:[0,1,0]
	v_fma_mix_f32 v86, v28, v39, v86 op_sel_hi:[0,1,0]
	v_fma_mix_f32 v85, v29, v39, v85 op_sel_hi:[0,1,0]
	v_fma_mix_f32 v86, v29, v40, v86 op_sel_hi:[0,1,0]
	v_fma_mix_f32 v85, v30, v40, v85 op_sel_hi:[0,1,0]
	v_fma_mix_f32 v86, v30, v41, v86 op_sel_hi:[0,1,0]
	v_fma_mix_f32 v85, v31, v41, v85 op_sel_hi:[0,1,0]
	v_fma_mix_f32 v86, v31, v42, v86 op_sel_hi:[0,1,0]
	v_fma_mix_f32 v85, v32, v42, v85 op_sel_hi:[0,1,0]
	v_fma_mix_f32 v86, v32, v43, v86 op_sel_hi:[0,1,0]
	v_fma_mix_f32 v85, v33, v43, v85 op_sel_hi:[0,1,0]
	v_fma_mix_f32 v86, v33, v44, v86 op_sel_hi:[0,1,0]
	v_fma_mix_f32 v85, v34, v44, v85 op_sel_hi:[0,1,0]
	v_fma_mix_f32 v86, v34, v45, v86 op_sel_hi:[0,1,0]
	v_fma_mix_f32 v85, v35, v45, v85 op_sel_hi:[0,1,0]
	v_fma_mix_f32 v86, v35, v46, v86 op_sel_hi:[0,1,0]
	v_fma_mix_f32 v85, v36, v46, v85 op_sel_hi:[0,1,0]
	v_fma_mix_f32 v86, v36, v47, v86 op_sel_hi:[0,1,0]
	ds_write2st64_b32 v8, v85, v86 offset0:72 offset1:80
	v_fma_mix_f32 v85, v4, v96, v37 op_sel_hi:[0,1,0]
	v_fma_mix_f32 v86, v4, v97, v37 op_sel_hi:[0,1,0]
	v_fma_mix_f32 v85, v5, v97, v85 op_sel_hi:[0,1,0]
	v_fma_mix_f32 v86, v5, v98, v86 op_sel_hi:[0,1,0]
	v_fma_mix_f32 v85, v6, v98, v85 op_sel_hi:[0,1,0]
	v_fma_mix_f32 v86, v6, v99, v86 op_sel_hi:[0,1,0]
	v_fma_mix_f32 v85, v7, v99, v85 op_sel_hi:[0,1,0]
	v_fma_mix_f32 v86, v7, v84, v86 op_sel_hi:[0,1,0]
	v_fma_mix_f32 v85, v9, v84, v85 op_sel_hi:[0,1,0]
	v_fma_mix_f32 v86, v9, v83, v86 op_sel_hi:[0,1,0]
	v_fma_mix_f32 v85, v10, v83, v85 op_sel_hi:[0,1,0]
	v_fma_mix_f32 v86, v10, v82, v86 op_sel_hi:[0,1,0]
	v_fma_mix_f32 v85, v11, v82, v85 op_sel_hi:[0,1,0]
	v_fma_mix_f32 v86, v11, v81, v86 op_sel_hi:[0,1,0]
	v_fma_mix_f32 v85, v12, v81, v85 op_sel_hi:[0,1,0]
	v_fma_mix_f32 v86, v12, v80, v86 op_sel_hi:[0,1,0]
	v_fma_mix_f32 v85, v13, v80, v85 op_sel_hi:[0,1,0]
	v_fma_mix_f32 v86, v13, v79, v86 op_sel_hi:[0,1,0]
	v_fma_mix_f32 v85, v14, v79, v85 op_sel_hi:[0,1,0]
	v_fma_mix_f32 v86, v14, v78, v86 op_sel_hi:[0,1,0]
	v_fma_mix_f32 v85, v15, v78, v85 op_sel_hi:[0,1,0]
	v_fma_mix_f32 v86, v15, v77, v86 op_sel_hi:[0,1,0]
	v_fma_mix_f32 v85, v16, v77, v85 op_sel_hi:[0,1,0]
	v_fma_mix_f32 v86, v16, v76, v86 op_sel_hi:[0,1,0]
	v_fma_mix_f32 v85, v17, v76, v85 op_sel_hi:[0,1,0]
	v_fma_mix_f32 v86, v17, v75, v86 op_sel_hi:[0,1,0]
	v_fma_mix_f32 v85, v18, v75, v85 op_sel_hi:[0,1,0]
	v_fma_mix_f32 v86, v18, v74, v86 op_sel_hi:[0,1,0]
	v_fma_mix_f32 v85, v19, v74, v85 op_sel_hi:[0,1,0]
	v_fma_mix_f32 v86, v19, v73, v86 op_sel_hi:[0,1,0]
	v_fma_mix_f32 v85, v21, v73, v85 op_sel_hi:[0,1,0]
	v_fma_mix_f32 v86, v21, v72, v86 op_sel_hi:[0,1,0]
	v_fma_mix_f32 v85, v22, v72, v85 op_sel_hi:[0,1,0]
	v_fma_mix_f32 v86, v22, v71, v86 op_sel_hi:[0,1,0]
	v_fma_mix_f32 v85, v23, v71, v85 op_sel_hi:[0,1,0]
	v_fma_mix_f32 v86, v23, v70, v86 op_sel_hi:[0,1,0]
	v_fma_mix_f32 v85, v24, v70, v85 op_sel_hi:[0,1,0]
	v_fma_mix_f32 v86, v24, v69, v86 op_sel_hi:[0,1,0]
	v_fma_mix_f32 v85, v25, v69, v85 op_sel_hi:[0,1,0]
	v_fma_mix_f32 v86, v25, v38, v86 op_sel_hi:[0,1,0]
	v_fma_mix_f32 v85, v26, v38, v85 op_sel_hi:[0,1,0]
	v_fma_mix_f32 v86, v26, v39, v86 op_sel_hi:[0,1,0]
	v_fma_mix_f32 v85, v27, v39, v85 op_sel_hi:[0,1,0]
	v_fma_mix_f32 v86, v27, v40, v86 op_sel_hi:[0,1,0]
	v_fma_mix_f32 v85, v28, v40, v85 op_sel_hi:[0,1,0]
	v_fma_mix_f32 v86, v28, v41, v86 op_sel_hi:[0,1,0]
	v_fma_mix_f32 v85, v29, v41, v85 op_sel_hi:[0,1,0]
	v_fma_mix_f32 v86, v29, v42, v86 op_sel_hi:[0,1,0]
	v_fma_mix_f32 v85, v30, v42, v85 op_sel_hi:[0,1,0]
	v_fma_mix_f32 v86, v30, v43, v86 op_sel_hi:[0,1,0]
	v_fma_mix_f32 v85, v31, v43, v85 op_sel_hi:[0,1,0]
	v_fma_mix_f32 v86, v31, v44, v86 op_sel_hi:[0,1,0]
	v_fma_mix_f32 v85, v32, v44, v85 op_sel_hi:[0,1,0]
	v_fma_mix_f32 v86, v32, v45, v86 op_sel_hi:[0,1,0]
	v_fma_mix_f32 v85, v33, v45, v85 op_sel_hi:[0,1,0]
	v_fma_mix_f32 v86, v33, v46, v86 op_sel_hi:[0,1,0]
	v_fma_mix_f32 v85, v34, v46, v85 op_sel_hi:[0,1,0]
	v_fma_mix_f32 v86, v34, v47, v86 op_sel_hi:[0,1,0]
	v_fma_mix_f32 v85, v35, v47, v85 op_sel_hi:[0,1,0]
	v_fma_mix_f32 v86, v35, v48, v86 op_sel_hi:[0,1,0]
	v_fma_mix_f32 v85, v36, v48, v85 op_sel_hi:[0,1,0]
	v_fma_mix_f32 v86, v36, v49, v86 op_sel_hi:[0,1,0]
	ds_write2st64_b32 v8, v85, v86 offset0:88 offset1:96
	v_fma_mix_f32 v85, v4, v98, v37 op_sel_hi:[0,1,0]
	v_fma_mix_f32 v85, v5, v99, v85 op_sel_hi:[0,1,0]
	v_fma_mix_f32 v86, v4, v99, v37 op_sel_hi:[0,1,0]
	v_fma_mix_f32 v85, v6, v84, v85 op_sel_hi:[0,1,0]
	v_fma_mix_f32 v86, v5, v84, v86 op_sel_hi:[0,1,0]
	v_fma_mix_f32 v84, v4, v84, v37 op_sel_hi:[0,1,0]
	v_fma_mix_f32 v85, v7, v83, v85 op_sel_hi:[0,1,0]
	v_fma_mix_f32 v86, v6, v83, v86 op_sel_hi:[0,1,0]
	v_fma_mix_f32 v84, v5, v83, v84 op_sel_hi:[0,1,0]
	v_fma_mix_f32 v83, v4, v83, v37 op_sel_hi:[0,1,0]
	v_fma_mix_f32 v85, v9, v82, v85 op_sel_hi:[0,1,0]
	v_fma_mix_f32 v86, v7, v82, v86 op_sel_hi:[0,1,0]
	v_fma_mix_f32 v84, v6, v82, v84 op_sel_hi:[0,1,0]
	v_fma_mix_f32 v83, v5, v82, v83 op_sel_hi:[0,1,0]
	v_fma_mix_f32 v82, v4, v82, v37 op_sel_hi:[0,1,0]
	v_fma_mix_f32 v85, v10, v81, v85 op_sel_hi:[0,1,0]
	v_fma_mix_f32 v86, v9, v81, v86 op_sel_hi:[0,1,0]
	v_fma_mix_f32 v84, v7, v81, v84 op_sel_hi:[0,1,0]
	v_fma_mix_f32 v83, v6, v81, v83 op_sel_hi:[0,1,0]
	v_fma_mix_f32 v82, v5, v81, v82 op_sel_hi:[0,1,0]
	v_fma_mix_f32 v81, v4, v81, v37 op_sel_hi:[0,1,0]
	v_fma_mix_f32 v85, v11, v80, v85 op_sel_hi:[0,1,0]
	v_fma_mix_f32 v86, v10, v80, v86 op_sel_hi:[0,1,0]
	v_fma_mix_f32 v84, v9, v80, v84 op_sel_hi:[0,1,0]
	v_fma_mix_f32 v83, v7, v80, v83 op_sel_hi:[0,1,0]
	v_fma_mix_f32 v82, v6, v80, v82 op_sel_hi:[0,1,0]
	v_fma_mix_f32 v81, v5, v80, v81 op_sel_hi:[0,1,0]
	v_fma_mix_f32 v80, v4, v80, v37 op_sel_hi:[0,1,0]
	v_fma_mix_f32 v85, v12, v79, v85 op_sel_hi:[0,1,0]
	v_fma_mix_f32 v86, v11, v79, v86 op_sel_hi:[0,1,0]
	v_fma_mix_f32 v84, v10, v79, v84 op_sel_hi:[0,1,0]
	v_fma_mix_f32 v83, v9, v79, v83 op_sel_hi:[0,1,0]
	v_fma_mix_f32 v82, v7, v79, v82 op_sel_hi:[0,1,0]
	v_fma_mix_f32 v81, v6, v79, v81 op_sel_hi:[0,1,0]
	v_fma_mix_f32 v80, v5, v79, v80 op_sel_hi:[0,1,0]
	v_fma_mix_f32 v79, v4, v79, v37 op_sel_hi:[0,1,0]
	v_fma_mix_f32 v85, v13, v78, v85 op_sel_hi:[0,1,0]
	v_fma_mix_f32 v86, v12, v78, v86 op_sel_hi:[0,1,0]
	v_fma_mix_f32 v84, v11, v78, v84 op_sel_hi:[0,1,0]
	v_fma_mix_f32 v83, v10, v78, v83 op_sel_hi:[0,1,0]
	v_fma_mix_f32 v82, v9, v78, v82 op_sel_hi:[0,1,0]
	v_fma_mix_f32 v81, v7, v78, v81 op_sel_hi:[0,1,0]
	v_fma_mix_f32 v80, v6, v78, v80 op_sel_hi:[0,1,0]
	v_fma_mix_f32 v79, v5, v78, v79 op_sel_hi:[0,1,0]
	v_fma_mix_f32 v78, v4, v78, v37 op_sel_hi:[0,1,0]
	v_fma_mix_f32 v85, v14, v77, v85 op_sel_hi:[0,1,0]
	v_fma_mix_f32 v86, v13, v77, v86 op_sel_hi:[0,1,0]
	v_fma_mix_f32 v84, v12, v77, v84 op_sel_hi:[0,1,0]
	v_fma_mix_f32 v83, v11, v77, v83 op_sel_hi:[0,1,0]
	v_fma_mix_f32 v82, v10, v77, v82 op_sel_hi:[0,1,0]
	v_fma_mix_f32 v81, v9, v77, v81 op_sel_hi:[0,1,0]
	v_fma_mix_f32 v80, v7, v77, v80 op_sel_hi:[0,1,0]
	v_fma_mix_f32 v79, v6, v77, v79 op_sel_hi:[0,1,0]
	v_fma_mix_f32 v78, v5, v77, v78 op_sel_hi:[0,1,0]
	v_fma_mix_f32 v77, v4, v77, v37 op_sel_hi:[0,1,0]
	v_fma_mix_f32 v85, v15, v76, v85 op_sel_hi:[0,1,0]
	v_fma_mix_f32 v86, v14, v76, v86 op_sel_hi:[0,1,0]
	v_fma_mix_f32 v84, v13, v76, v84 op_sel_hi:[0,1,0]
	v_fma_mix_f32 v83, v12, v76, v83 op_sel_hi:[0,1,0]
	v_fma_mix_f32 v82, v11, v76, v82 op_sel_hi:[0,1,0]
	v_fma_mix_f32 v81, v10, v76, v81 op_sel_hi:[0,1,0]
	v_fma_mix_f32 v80, v9, v76, v80 op_sel_hi:[0,1,0]
	v_fma_mix_f32 v79, v7, v76, v79 op_sel_hi:[0,1,0]
	v_fma_mix_f32 v78, v6, v76, v78 op_sel_hi:[0,1,0]
	v_fma_mix_f32 v77, v5, v76, v77 op_sel_hi:[0,1,0]
	v_fma_mix_f32 v76, v4, v76, v37 op_sel_hi:[0,1,0]
	v_fma_mix_f32 v85, v16, v75, v85 op_sel_hi:[0,1,0]
	v_fma_mix_f32 v86, v15, v75, v86 op_sel_hi:[0,1,0]
	v_fma_mix_f32 v84, v14, v75, v84 op_sel_hi:[0,1,0]
	v_fma_mix_f32 v83, v13, v75, v83 op_sel_hi:[0,1,0]
	v_fma_mix_f32 v82, v12, v75, v82 op_sel_hi:[0,1,0]
	v_fma_mix_f32 v81, v11, v75, v81 op_sel_hi:[0,1,0]
	v_fma_mix_f32 v80, v10, v75, v80 op_sel_hi:[0,1,0]
	v_fma_mix_f32 v79, v9, v75, v79 op_sel_hi:[0,1,0]
	v_fma_mix_f32 v78, v7, v75, v78 op_sel_hi:[0,1,0]
	v_fma_mix_f32 v77, v6, v75, v77 op_sel_hi:[0,1,0]
	v_fma_mix_f32 v76, v5, v75, v76 op_sel_hi:[0,1,0]
	v_fma_mix_f32 v75, v4, v75, v37 op_sel_hi:[0,1,0]
	v_fma_mix_f32 v85, v17, v74, v85 op_sel_hi:[0,1,0]
	v_fma_mix_f32 v86, v16, v74, v86 op_sel_hi:[0,1,0]
	v_fma_mix_f32 v84, v15, v74, v84 op_sel_hi:[0,1,0]
	v_fma_mix_f32 v83, v14, v74, v83 op_sel_hi:[0,1,0]
	v_fma_mix_f32 v82, v13, v74, v82 op_sel_hi:[0,1,0]
	v_fma_mix_f32 v81, v12, v74, v81 op_sel_hi:[0,1,0]
	v_fma_mix_f32 v80, v11, v74, v80 op_sel_hi:[0,1,0]
	v_fma_mix_f32 v79, v10, v74, v79 op_sel_hi:[0,1,0]
	v_fma_mix_f32 v78, v9, v74, v78 op_sel_hi:[0,1,0]
	v_fma_mix_f32 v77, v7, v74, v77 op_sel_hi:[0,1,0]
	v_fma_mix_f32 v76, v6, v74, v76 op_sel_hi:[0,1,0]
	v_fma_mix_f32 v75, v5, v74, v75 op_sel_hi:[0,1,0]
	v_fma_mix_f32 v74, v4, v74, v37 op_sel_hi:[0,1,0]
	v_fma_mix_f32 v85, v18, v73, v85 op_sel_hi:[0,1,0]
	v_fma_mix_f32 v86, v17, v73, v86 op_sel_hi:[0,1,0]
	v_fma_mix_f32 v84, v16, v73, v84 op_sel_hi:[0,1,0]
	v_fma_mix_f32 v83, v15, v73, v83 op_sel_hi:[0,1,0]
	v_fma_mix_f32 v82, v14, v73, v82 op_sel_hi:[0,1,0]
	v_fma_mix_f32 v81, v13, v73, v81 op_sel_hi:[0,1,0]
	v_fma_mix_f32 v80, v12, v73, v80 op_sel_hi:[0,1,0]
	v_fma_mix_f32 v79, v11, v73, v79 op_sel_hi:[0,1,0]
	v_fma_mix_f32 v78, v10, v73, v78 op_sel_hi:[0,1,0]
	v_fma_mix_f32 v77, v9, v73, v77 op_sel_hi:[0,1,0]
	v_fma_mix_f32 v76, v7, v73, v76 op_sel_hi:[0,1,0]
	v_fma_mix_f32 v75, v6, v73, v75 op_sel_hi:[0,1,0]
	v_fma_mix_f32 v74, v5, v73, v74 op_sel_hi:[0,1,0]
	v_fma_mix_f32 v73, v4, v73, v37 op_sel_hi:[0,1,0]
	v_fma_mix_f32 v85, v19, v72, v85 op_sel_hi:[0,1,0]
	v_fma_mix_f32 v86, v18, v72, v86 op_sel_hi:[0,1,0]
	v_fma_mix_f32 v84, v17, v72, v84 op_sel_hi:[0,1,0]
	v_fma_mix_f32 v83, v16, v72, v83 op_sel_hi:[0,1,0]
	v_fma_mix_f32 v82, v15, v72, v82 op_sel_hi:[0,1,0]
	v_fma_mix_f32 v81, v14, v72, v81 op_sel_hi:[0,1,0]
	v_fma_mix_f32 v80, v13, v72, v80 op_sel_hi:[0,1,0]
	v_fma_mix_f32 v79, v12, v72, v79 op_sel_hi:[0,1,0]
	v_fma_mix_f32 v78, v11, v72, v78 op_sel_hi:[0,1,0]
	v_fma_mix_f32 v77, v10, v72, v77 op_sel_hi:[0,1,0]
	v_fma_mix_f32 v76, v9, v72, v76 op_sel_hi:[0,1,0]
	v_fma_mix_f32 v75, v7, v72, v75 op_sel_hi:[0,1,0]
	v_fma_mix_f32 v74, v6, v72, v74 op_sel_hi:[0,1,0]
	v_fma_mix_f32 v73, v5, v72, v73 op_sel_hi:[0,1,0]
	v_fma_mix_f32 v72, v4, v72, v37 op_sel_hi:[0,1,0]
	v_fma_mix_f32 v85, v21, v71, v85 op_sel_hi:[0,1,0]
	v_fma_mix_f32 v86, v19, v71, v86 op_sel_hi:[0,1,0]
	v_fma_mix_f32 v84, v18, v71, v84 op_sel_hi:[0,1,0]
	v_fma_mix_f32 v83, v17, v71, v83 op_sel_hi:[0,1,0]
	v_fma_mix_f32 v82, v16, v71, v82 op_sel_hi:[0,1,0]
	v_fma_mix_f32 v81, v15, v71, v81 op_sel_hi:[0,1,0]
	v_fma_mix_f32 v80, v14, v71, v80 op_sel_hi:[0,1,0]
	v_fma_mix_f32 v79, v13, v71, v79 op_sel_hi:[0,1,0]
	v_fma_mix_f32 v78, v12, v71, v78 op_sel_hi:[0,1,0]
	v_fma_mix_f32 v77, v11, v71, v77 op_sel_hi:[0,1,0]
	v_fma_mix_f32 v76, v10, v71, v76 op_sel_hi:[0,1,0]
	v_fma_mix_f32 v75, v9, v71, v75 op_sel_hi:[0,1,0]
	v_fma_mix_f32 v74, v7, v71, v74 op_sel_hi:[0,1,0]
	v_fma_mix_f32 v73, v6, v71, v73 op_sel_hi:[0,1,0]
	v_fma_mix_f32 v72, v5, v71, v72 op_sel_hi:[0,1,0]
	v_fma_mix_f32 v71, v4, v71, v37 op_sel_hi:[0,1,0]
	v_fma_mix_f32 v85, v22, v70, v85 op_sel_hi:[0,1,0]
	v_fma_mix_f32 v86, v21, v70, v86 op_sel_hi:[0,1,0]
	v_fma_mix_f32 v84, v19, v70, v84 op_sel_hi:[0,1,0]
	v_fma_mix_f32 v83, v18, v70, v83 op_sel_hi:[0,1,0]
	v_fma_mix_f32 v82, v17, v70, v82 op_sel_hi:[0,1,0]
	v_fma_mix_f32 v81, v16, v70, v81 op_sel_hi:[0,1,0]
	v_fma_mix_f32 v80, v15, v70, v80 op_sel_hi:[0,1,0]
	v_fma_mix_f32 v79, v14, v70, v79 op_sel_hi:[0,1,0]
	v_fma_mix_f32 v78, v13, v70, v78 op_sel_hi:[0,1,0]
	v_fma_mix_f32 v77, v12, v70, v77 op_sel_hi:[0,1,0]
	v_fma_mix_f32 v76, v11, v70, v76 op_sel_hi:[0,1,0]
	v_fma_mix_f32 v75, v10, v70, v75 op_sel_hi:[0,1,0]
	v_fma_mix_f32 v74, v9, v70, v74 op_sel_hi:[0,1,0]
	v_fma_mix_f32 v73, v7, v70, v73 op_sel_hi:[0,1,0]
	v_fma_mix_f32 v72, v6, v70, v72 op_sel_hi:[0,1,0]
	v_fma_mix_f32 v71, v5, v70, v71 op_sel_hi:[0,1,0]
	v_fma_mix_f32 v70, v4, v70, v37 op_sel_hi:[0,1,0]
	v_fma_mix_f32 v85, v23, v69, v85 op_sel_hi:[0,1,0]
	v_fma_mix_f32 v86, v22, v69, v86 op_sel_hi:[0,1,0]
	v_fma_mix_f32 v84, v21, v69, v84 op_sel_hi:[0,1,0]
	v_fma_mix_f32 v83, v19, v69, v83 op_sel_hi:[0,1,0]
	v_fma_mix_f32 v82, v18, v69, v82 op_sel_hi:[0,1,0]
	v_fma_mix_f32 v81, v17, v69, v81 op_sel_hi:[0,1,0]
	v_fma_mix_f32 v80, v16, v69, v80 op_sel_hi:[0,1,0]
	v_fma_mix_f32 v79, v15, v69, v79 op_sel_hi:[0,1,0]
	v_fma_mix_f32 v78, v14, v69, v78 op_sel_hi:[0,1,0]
	v_fma_mix_f32 v77, v13, v69, v77 op_sel_hi:[0,1,0]
	v_fma_mix_f32 v76, v12, v69, v76 op_sel_hi:[0,1,0]
	v_fma_mix_f32 v75, v11, v69, v75 op_sel_hi:[0,1,0]
	v_fma_mix_f32 v74, v10, v69, v74 op_sel_hi:[0,1,0]
	v_fma_mix_f32 v73, v9, v69, v73 op_sel_hi:[0,1,0]
	v_fma_mix_f32 v72, v7, v69, v72 op_sel_hi:[0,1,0]
	v_fma_mix_f32 v71, v6, v69, v71 op_sel_hi:[0,1,0]
	v_fma_mix_f32 v70, v5, v69, v70 op_sel_hi:[0,1,0]
	v_fma_mix_f32 v69, v4, v69, v37 op_sel_hi:[0,1,0]
	v_fma_mix_f32 v4, v4, v38, v37 op_sel_hi:[0,1,0]
	v_fma_mix_f32 v69, v5, v38, v69 op_sel_hi:[0,1,0]
	v_fma_mix_f32 v4, v5, v39, v4 op_sel_hi:[0,1,0]
	v_fma_mix_f32 v70, v6, v38, v70 op_sel_hi:[0,1,0]
	v_fma_mix_f32 v69, v6, v39, v69 op_sel_hi:[0,1,0]
	v_fma_mix_f32 v4, v6, v40, v4 op_sel_hi:[0,1,0]
	v_fma_mix_f32 v71, v7, v38, v71 op_sel_hi:[0,1,0]
	v_fma_mix_f32 v70, v7, v39, v70 op_sel_hi:[0,1,0]
	v_fma_mix_f32 v69, v7, v40, v69 op_sel_hi:[0,1,0]
	v_fma_mix_f32 v4, v7, v41, v4 op_sel_hi:[0,1,0]
	v_fma_mix_f32 v72, v9, v38, v72 op_sel_hi:[0,1,0]
	v_fma_mix_f32 v71, v9, v39, v71 op_sel_hi:[0,1,0]
	v_fma_mix_f32 v70, v9, v40, v70 op_sel_hi:[0,1,0]
	v_fma_mix_f32 v69, v9, v41, v69 op_sel_hi:[0,1,0]
	v_fma_mix_f32 v4, v9, v42, v4 op_sel_hi:[0,1,0]
	v_fma_mix_f32 v73, v10, v38, v73 op_sel_hi:[0,1,0]
	v_fma_mix_f32 v72, v10, v39, v72 op_sel_hi:[0,1,0]
	v_fma_mix_f32 v71, v10, v40, v71 op_sel_hi:[0,1,0]
	v_fma_mix_f32 v70, v10, v41, v70 op_sel_hi:[0,1,0]
	v_fma_mix_f32 v69, v10, v42, v69 op_sel_hi:[0,1,0]
	v_fma_mix_f32 v4, v10, v43, v4 op_sel_hi:[0,1,0]
	v_fma_mix_f32 v74, v11, v38, v74 op_sel_hi:[0,1,0]
	v_fma_mix_f32 v73, v11, v39, v73 op_sel_hi:[0,1,0]
	v_fma_mix_f32 v72, v11, v40, v72 op_sel_hi:[0,1,0]
	v_fma_mix_f32 v71, v11, v41, v71 op_sel_hi:[0,1,0]
	v_fma_mix_f32 v70, v11, v42, v70 op_sel_hi:[0,1,0]
	v_fma_mix_f32 v69, v11, v43, v69 op_sel_hi:[0,1,0]
	v_fma_mix_f32 v4, v11, v44, v4 op_sel_hi:[0,1,0]
	v_fma_mix_f32 v75, v12, v38, v75 op_sel_hi:[0,1,0]
	v_fma_mix_f32 v74, v12, v39, v74 op_sel_hi:[0,1,0]
	v_fma_mix_f32 v73, v12, v40, v73 op_sel_hi:[0,1,0]
	v_fma_mix_f32 v72, v12, v41, v72 op_sel_hi:[0,1,0]
	v_fma_mix_f32 v71, v12, v42, v71 op_sel_hi:[0,1,0]
	v_fma_mix_f32 v70, v12, v43, v70 op_sel_hi:[0,1,0]
	v_fma_mix_f32 v69, v12, v44, v69 op_sel_hi:[0,1,0]
	v_fma_mix_f32 v4, v12, v45, v4 op_sel_hi:[0,1,0]
	v_fma_mix_f32 v76, v13, v38, v76 op_sel_hi:[0,1,0]
	v_fma_mix_f32 v75, v13, v39, v75 op_sel_hi:[0,1,0]
	v_fma_mix_f32 v74, v13, v40, v74 op_sel_hi:[0,1,0]
	v_fma_mix_f32 v73, v13, v41, v73 op_sel_hi:[0,1,0]
	v_fma_mix_f32 v72, v13, v42, v72 op_sel_hi:[0,1,0]
	v_fma_mix_f32 v71, v13, v43, v71 op_sel_hi:[0,1,0]
	v_fma_mix_f32 v70, v13, v44, v70 op_sel_hi:[0,1,0]
	v_fma_mix_f32 v69, v13, v45, v69 op_sel_hi:[0,1,0]
	v_fma_mix_f32 v4, v13, v46, v4 op_sel_hi:[0,1,0]
	v_fma_mix_f32 v77, v14, v38, v77 op_sel_hi:[0,1,0]
	v_fma_mix_f32 v76, v14, v39, v76 op_sel_hi:[0,1,0]
	v_fma_mix_f32 v75, v14, v40, v75 op_sel_hi:[0,1,0]
	v_fma_mix_f32 v74, v14, v41, v74 op_sel_hi:[0,1,0]
	v_fma_mix_f32 v73, v14, v42, v73 op_sel_hi:[0,1,0]
	v_fma_mix_f32 v72, v14, v43, v72 op_sel_hi:[0,1,0]
	v_fma_mix_f32 v71, v14, v44, v71 op_sel_hi:[0,1,0]
	v_fma_mix_f32 v70, v14, v45, v70 op_sel_hi:[0,1,0]
	v_fma_mix_f32 v69, v14, v46, v69 op_sel_hi:[0,1,0]
	v_fma_mix_f32 v4, v14, v47, v4 op_sel_hi:[0,1,0]
	v_fma_mix_f32 v78, v15, v38, v78 op_sel_hi:[0,1,0]
	v_fma_mix_f32 v77, v15, v39, v77 op_sel_hi:[0,1,0]
	v_fma_mix_f32 v76, v15, v40, v76 op_sel_hi:[0,1,0]
	v_fma_mix_f32 v75, v15, v41, v75 op_sel_hi:[0,1,0]
	v_fma_mix_f32 v74, v15, v42, v74 op_sel_hi:[0,1,0]
	v_fma_mix_f32 v73, v15, v43, v73 op_sel_hi:[0,1,0]
	v_fma_mix_f32 v72, v15, v44, v72 op_sel_hi:[0,1,0]
	v_fma_mix_f32 v71, v15, v45, v71 op_sel_hi:[0,1,0]
	v_fma_mix_f32 v70, v15, v46, v70 op_sel_hi:[0,1,0]
	v_fma_mix_f32 v69, v15, v47, v69 op_sel_hi:[0,1,0]
	v_fma_mix_f32 v4, v15, v48, v4 op_sel_hi:[0,1,0]
	v_fma_mix_f32 v79, v16, v38, v79 op_sel_hi:[0,1,0]
	v_fma_mix_f32 v78, v16, v39, v78 op_sel_hi:[0,1,0]
	v_fma_mix_f32 v77, v16, v40, v77 op_sel_hi:[0,1,0]
	v_fma_mix_f32 v76, v16, v41, v76 op_sel_hi:[0,1,0]
	v_fma_mix_f32 v75, v16, v42, v75 op_sel_hi:[0,1,0]
	v_fma_mix_f32 v74, v16, v43, v74 op_sel_hi:[0,1,0]
	v_fma_mix_f32 v73, v16, v44, v73 op_sel_hi:[0,1,0]
	v_fma_mix_f32 v72, v16, v45, v72 op_sel_hi:[0,1,0]
	v_fma_mix_f32 v71, v16, v46, v71 op_sel_hi:[0,1,0]
	v_fma_mix_f32 v70, v16, v47, v70 op_sel_hi:[0,1,0]
	v_fma_mix_f32 v69, v16, v48, v69 op_sel_hi:[0,1,0]
	v_fma_mix_f32 v4, v16, v49, v4 op_sel_hi:[0,1,0]
	v_fma_mix_f32 v80, v17, v38, v80 op_sel_hi:[0,1,0]
	v_fma_mix_f32 v79, v17, v39, v79 op_sel_hi:[0,1,0]
	v_fma_mix_f32 v78, v17, v40, v78 op_sel_hi:[0,1,0]
	v_fma_mix_f32 v77, v17, v41, v77 op_sel_hi:[0,1,0]
	v_fma_mix_f32 v76, v17, v42, v76 op_sel_hi:[0,1,0]
	v_fma_mix_f32 v75, v17, v43, v75 op_sel_hi:[0,1,0]
	v_fma_mix_f32 v74, v17, v44, v74 op_sel_hi:[0,1,0]
	v_fma_mix_f32 v73, v17, v45, v73 op_sel_hi:[0,1,0]
	v_fma_mix_f32 v72, v17, v46, v72 op_sel_hi:[0,1,0]
	v_fma_mix_f32 v71, v17, v47, v71 op_sel_hi:[0,1,0]
	v_fma_mix_f32 v70, v17, v48, v70 op_sel_hi:[0,1,0]
	v_fma_mix_f32 v69, v17, v49, v69 op_sel_hi:[0,1,0]
	v_fma_mix_f32 v4, v17, v50, v4 op_sel_hi:[0,1,0]
	v_fma_mix_f32 v81, v18, v38, v81 op_sel_hi:[0,1,0]
	v_fma_mix_f32 v80, v18, v39, v80 op_sel_hi:[0,1,0]
	v_fma_mix_f32 v79, v18, v40, v79 op_sel_hi:[0,1,0]
	v_fma_mix_f32 v78, v18, v41, v78 op_sel_hi:[0,1,0]
	v_fma_mix_f32 v77, v18, v42, v77 op_sel_hi:[0,1,0]
	v_fma_mix_f32 v76, v18, v43, v76 op_sel_hi:[0,1,0]
	v_fma_mix_f32 v75, v18, v44, v75 op_sel_hi:[0,1,0]
	v_fma_mix_f32 v74, v18, v45, v74 op_sel_hi:[0,1,0]
	v_fma_mix_f32 v73, v18, v46, v73 op_sel_hi:[0,1,0]
	v_fma_mix_f32 v72, v18, v47, v72 op_sel_hi:[0,1,0]
	v_fma_mix_f32 v71, v18, v48, v71 op_sel_hi:[0,1,0]
	v_fma_mix_f32 v70, v18, v49, v70 op_sel_hi:[0,1,0]
	v_fma_mix_f32 v69, v18, v50, v69 op_sel_hi:[0,1,0]
	v_fma_mix_f32 v4, v18, v51, v4 op_sel_hi:[0,1,0]
	v_fma_mix_f32 v82, v19, v38, v82 op_sel_hi:[0,1,0]
	v_fma_mix_f32 v81, v19, v39, v81 op_sel_hi:[0,1,0]
	v_fma_mix_f32 v80, v19, v40, v80 op_sel_hi:[0,1,0]
	v_fma_mix_f32 v79, v19, v41, v79 op_sel_hi:[0,1,0]
	v_fma_mix_f32 v78, v19, v42, v78 op_sel_hi:[0,1,0]
	v_fma_mix_f32 v77, v19, v43, v77 op_sel_hi:[0,1,0]
	v_fma_mix_f32 v76, v19, v44, v76 op_sel_hi:[0,1,0]
	v_fma_mix_f32 v75, v19, v45, v75 op_sel_hi:[0,1,0]
	v_fma_mix_f32 v74, v19, v46, v74 op_sel_hi:[0,1,0]
	v_fma_mix_f32 v73, v19, v47, v73 op_sel_hi:[0,1,0]
	v_fma_mix_f32 v72, v19, v48, v72 op_sel_hi:[0,1,0]
	v_fma_mix_f32 v71, v19, v49, v71 op_sel_hi:[0,1,0]
	v_fma_mix_f32 v70, v19, v50, v70 op_sel_hi:[0,1,0]
	v_fma_mix_f32 v69, v19, v51, v69 op_sel_hi:[0,1,0]
	v_fma_mix_f32 v4, v19, v52, v4 op_sel_hi:[0,1,0]
	v_fma_mix_f32 v83, v21, v38, v83 op_sel_hi:[0,1,0]
	v_fma_mix_f32 v82, v21, v39, v82 op_sel_hi:[0,1,0]
	v_fma_mix_f32 v81, v21, v40, v81 op_sel_hi:[0,1,0]
	v_fma_mix_f32 v80, v21, v41, v80 op_sel_hi:[0,1,0]
	v_fma_mix_f32 v79, v21, v42, v79 op_sel_hi:[0,1,0]
	v_fma_mix_f32 v78, v21, v43, v78 op_sel_hi:[0,1,0]
	v_fma_mix_f32 v77, v21, v44, v77 op_sel_hi:[0,1,0]
	v_fma_mix_f32 v76, v21, v45, v76 op_sel_hi:[0,1,0]
	v_fma_mix_f32 v75, v21, v46, v75 op_sel_hi:[0,1,0]
	v_fma_mix_f32 v74, v21, v47, v74 op_sel_hi:[0,1,0]
	v_fma_mix_f32 v73, v21, v48, v73 op_sel_hi:[0,1,0]
	v_fma_mix_f32 v72, v21, v49, v72 op_sel_hi:[0,1,0]
	v_fma_mix_f32 v71, v21, v50, v71 op_sel_hi:[0,1,0]
	v_fma_mix_f32 v70, v21, v51, v70 op_sel_hi:[0,1,0]
	v_fma_mix_f32 v69, v21, v52, v69 op_sel_hi:[0,1,0]
	v_fma_mix_f32 v4, v21, v53, v4 op_sel_hi:[0,1,0]
	v_fma_mix_f32 v84, v22, v38, v84 op_sel_hi:[0,1,0]
	v_fma_mix_f32 v83, v22, v39, v83 op_sel_hi:[0,1,0]
	v_fma_mix_f32 v82, v22, v40, v82 op_sel_hi:[0,1,0]
	v_fma_mix_f32 v81, v22, v41, v81 op_sel_hi:[0,1,0]
	v_fma_mix_f32 v80, v22, v42, v80 op_sel_hi:[0,1,0]
	v_fma_mix_f32 v79, v22, v43, v79 op_sel_hi:[0,1,0]
	v_fma_mix_f32 v78, v22, v44, v78 op_sel_hi:[0,1,0]
	v_fma_mix_f32 v77, v22, v45, v77 op_sel_hi:[0,1,0]
	v_fma_mix_f32 v76, v22, v46, v76 op_sel_hi:[0,1,0]
	v_fma_mix_f32 v75, v22, v47, v75 op_sel_hi:[0,1,0]
	v_fma_mix_f32 v74, v22, v48, v74 op_sel_hi:[0,1,0]
	v_fma_mix_f32 v73, v22, v49, v73 op_sel_hi:[0,1,0]
	v_fma_mix_f32 v72, v22, v50, v72 op_sel_hi:[0,1,0]
	v_fma_mix_f32 v71, v22, v51, v71 op_sel_hi:[0,1,0]
	v_fma_mix_f32 v70, v22, v52, v70 op_sel_hi:[0,1,0]
	v_fma_mix_f32 v69, v22, v53, v69 op_sel_hi:[0,1,0]
	v_fma_mix_f32 v4, v22, v54, v4 op_sel_hi:[0,1,0]
	v_fma_mix_f32 v86, v23, v38, v86 op_sel_hi:[0,1,0]
	v_fma_mix_f32 v84, v23, v39, v84 op_sel_hi:[0,1,0]
	v_fma_mix_f32 v83, v23, v40, v83 op_sel_hi:[0,1,0]
	v_fma_mix_f32 v82, v23, v41, v82 op_sel_hi:[0,1,0]
	v_fma_mix_f32 v81, v23, v42, v81 op_sel_hi:[0,1,0]
	v_fma_mix_f32 v80, v23, v43, v80 op_sel_hi:[0,1,0]
	v_fma_mix_f32 v79, v23, v44, v79 op_sel_hi:[0,1,0]
	v_fma_mix_f32 v78, v23, v45, v78 op_sel_hi:[0,1,0]
	v_fma_mix_f32 v77, v23, v46, v77 op_sel_hi:[0,1,0]
	v_fma_mix_f32 v76, v23, v47, v76 op_sel_hi:[0,1,0]
	v_fma_mix_f32 v75, v23, v48, v75 op_sel_hi:[0,1,0]
	v_fma_mix_f32 v74, v23, v49, v74 op_sel_hi:[0,1,0]
	v_fma_mix_f32 v73, v23, v50, v73 op_sel_hi:[0,1,0]
	v_fma_mix_f32 v72, v23, v51, v72 op_sel_hi:[0,1,0]
	v_fma_mix_f32 v71, v23, v52, v71 op_sel_hi:[0,1,0]
	v_fma_mix_f32 v70, v23, v53, v70 op_sel_hi:[0,1,0]
	v_fma_mix_f32 v69, v23, v54, v69 op_sel_hi:[0,1,0]
	s_waitcnt lgkmcnt(14)
	v_fma_mix_f32 v4, v23, v55, v4 op_sel_hi:[0,1,0]
	v_fma_mix_f32 v85, v24, v38, v85 op_sel_hi:[0,1,0]
	v_fma_mix_f32 v86, v24, v39, v86 op_sel_hi:[0,1,0]
	v_fma_mix_f32 v84, v24, v40, v84 op_sel_hi:[0,1,0]
	v_fma_mix_f32 v83, v24, v41, v83 op_sel_hi:[0,1,0]
	v_fma_mix_f32 v82, v24, v42, v82 op_sel_hi:[0,1,0]
	v_fma_mix_f32 v81, v24, v43, v81 op_sel_hi:[0,1,0]
	v_fma_mix_f32 v80, v24, v44, v80 op_sel_hi:[0,1,0]
	v_fma_mix_f32 v79, v24, v45, v79 op_sel_hi:[0,1,0]
	v_fma_mix_f32 v78, v24, v46, v78 op_sel_hi:[0,1,0]
	v_fma_mix_f32 v77, v24, v47, v77 op_sel_hi:[0,1,0]
	v_fma_mix_f32 v76, v24, v48, v76 op_sel_hi:[0,1,0]
	v_fma_mix_f32 v75, v24, v49, v75 op_sel_hi:[0,1,0]
	v_fma_mix_f32 v74, v24, v50, v74 op_sel_hi:[0,1,0]
	v_fma_mix_f32 v73, v24, v51, v73 op_sel_hi:[0,1,0]
	v_fma_mix_f32 v72, v24, v52, v72 op_sel_hi:[0,1,0]
	v_fma_mix_f32 v71, v24, v53, v71 op_sel_hi:[0,1,0]
	v_fma_mix_f32 v70, v24, v54, v70 op_sel_hi:[0,1,0]
	v_fma_mix_f32 v69, v24, v55, v69 op_sel_hi:[0,1,0]
	v_fma_mix_f32 v4, v24, v56, v4 op_sel_hi:[0,1,0]
	v_fma_mix_f32 v85, v25, v39, v85 op_sel_hi:[0,1,0]
	v_fma_mix_f32 v86, v25, v40, v86 op_sel_hi:[0,1,0]
	v_fma_mix_f32 v84, v25, v41, v84 op_sel_hi:[0,1,0]
	v_fma_mix_f32 v83, v25, v42, v83 op_sel_hi:[0,1,0]
	v_fma_mix_f32 v82, v25, v43, v82 op_sel_hi:[0,1,0]
	v_fma_mix_f32 v81, v25, v44, v81 op_sel_hi:[0,1,0]
	v_fma_mix_f32 v80, v25, v45, v80 op_sel_hi:[0,1,0]
	v_fma_mix_f32 v79, v25, v46, v79 op_sel_hi:[0,1,0]
	v_fma_mix_f32 v78, v25, v47, v78 op_sel_hi:[0,1,0]
	v_fma_mix_f32 v77, v25, v48, v77 op_sel_hi:[0,1,0]
	v_fma_mix_f32 v76, v25, v49, v76 op_sel_hi:[0,1,0]
	v_fma_mix_f32 v75, v25, v50, v75 op_sel_hi:[0,1,0]
	v_fma_mix_f32 v74, v25, v51, v74 op_sel_hi:[0,1,0]
	v_fma_mix_f32 v73, v25, v52, v73 op_sel_hi:[0,1,0]
	v_fma_mix_f32 v72, v25, v53, v72 op_sel_hi:[0,1,0]
	v_fma_mix_f32 v71, v25, v54, v71 op_sel_hi:[0,1,0]
	v_fma_mix_f32 v70, v25, v55, v70 op_sel_hi:[0,1,0]
	v_fma_mix_f32 v69, v25, v56, v69 op_sel_hi:[0,1,0]
	v_fma_mix_f32 v4, v25, v57, v4 op_sel_hi:[0,1,0]
	v_fma_mix_f32 v85, v26, v40, v85 op_sel_hi:[0,1,0]
	v_fma_mix_f32 v86, v26, v41, v86 op_sel_hi:[0,1,0]
	v_fma_mix_f32 v84, v26, v42, v84 op_sel_hi:[0,1,0]
	v_fma_mix_f32 v83, v26, v43, v83 op_sel_hi:[0,1,0]
	v_fma_mix_f32 v82, v26, v44, v82 op_sel_hi:[0,1,0]
	v_fma_mix_f32 v81, v26, v45, v81 op_sel_hi:[0,1,0]
	v_fma_mix_f32 v80, v26, v46, v80 op_sel_hi:[0,1,0]
	v_fma_mix_f32 v79, v26, v47, v79 op_sel_hi:[0,1,0]
	v_fma_mix_f32 v78, v26, v48, v78 op_sel_hi:[0,1,0]
	v_fma_mix_f32 v77, v26, v49, v77 op_sel_hi:[0,1,0]
	v_fma_mix_f32 v76, v26, v50, v76 op_sel_hi:[0,1,0]
	v_fma_mix_f32 v75, v26, v51, v75 op_sel_hi:[0,1,0]
	v_fma_mix_f32 v74, v26, v52, v74 op_sel_hi:[0,1,0]
	v_fma_mix_f32 v73, v26, v53, v73 op_sel_hi:[0,1,0]
	v_fma_mix_f32 v72, v26, v54, v72 op_sel_hi:[0,1,0]
	v_fma_mix_f32 v71, v26, v55, v71 op_sel_hi:[0,1,0]
	v_fma_mix_f32 v70, v26, v56, v70 op_sel_hi:[0,1,0]
	v_fma_mix_f32 v69, v26, v57, v69 op_sel_hi:[0,1,0]
	v_fma_mix_f32 v4, v26, v58, v4 op_sel_hi:[0,1,0]
	v_fma_mix_f32 v85, v27, v41, v85 op_sel_hi:[0,1,0]
	v_fma_mix_f32 v86, v27, v42, v86 op_sel_hi:[0,1,0]
	v_fma_mix_f32 v84, v27, v43, v84 op_sel_hi:[0,1,0]
	v_fma_mix_f32 v83, v27, v44, v83 op_sel_hi:[0,1,0]
	v_fma_mix_f32 v82, v27, v45, v82 op_sel_hi:[0,1,0]
	v_fma_mix_f32 v81, v27, v46, v81 op_sel_hi:[0,1,0]
	v_fma_mix_f32 v80, v27, v47, v80 op_sel_hi:[0,1,0]
	v_fma_mix_f32 v79, v27, v48, v79 op_sel_hi:[0,1,0]
	v_fma_mix_f32 v78, v27, v49, v78 op_sel_hi:[0,1,0]
	v_fma_mix_f32 v77, v27, v50, v77 op_sel_hi:[0,1,0]
	v_fma_mix_f32 v76, v27, v51, v76 op_sel_hi:[0,1,0]
	v_fma_mix_f32 v75, v27, v52, v75 op_sel_hi:[0,1,0]
	v_fma_mix_f32 v74, v27, v53, v74 op_sel_hi:[0,1,0]
	v_fma_mix_f32 v73, v27, v54, v73 op_sel_hi:[0,1,0]
	v_fma_mix_f32 v72, v27, v55, v72 op_sel_hi:[0,1,0]
	v_fma_mix_f32 v71, v27, v56, v71 op_sel_hi:[0,1,0]
	v_fma_mix_f32 v70, v27, v57, v70 op_sel_hi:[0,1,0]
	v_fma_mix_f32 v69, v27, v58, v69 op_sel_hi:[0,1,0]
	v_fma_mix_f32 v4, v27, v59, v4 op_sel_hi:[0,1,0]
	v_fma_mix_f32 v85, v28, v42, v85 op_sel_hi:[0,1,0]
	v_fma_mix_f32 v86, v28, v43, v86 op_sel_hi:[0,1,0]
	v_fma_mix_f32 v84, v28, v44, v84 op_sel_hi:[0,1,0]
	v_fma_mix_f32 v83, v28, v45, v83 op_sel_hi:[0,1,0]
	v_fma_mix_f32 v82, v28, v46, v82 op_sel_hi:[0,1,0]
	v_fma_mix_f32 v81, v28, v47, v81 op_sel_hi:[0,1,0]
	v_fma_mix_f32 v80, v28, v48, v80 op_sel_hi:[0,1,0]
	v_fma_mix_f32 v79, v28, v49, v79 op_sel_hi:[0,1,0]
	v_fma_mix_f32 v78, v28, v50, v78 op_sel_hi:[0,1,0]
	v_fma_mix_f32 v77, v28, v51, v77 op_sel_hi:[0,1,0]
	v_fma_mix_f32 v76, v28, v52, v76 op_sel_hi:[0,1,0]
	v_fma_mix_f32 v75, v28, v53, v75 op_sel_hi:[0,1,0]
	v_fma_mix_f32 v74, v28, v54, v74 op_sel_hi:[0,1,0]
	v_fma_mix_f32 v73, v28, v55, v73 op_sel_hi:[0,1,0]
	v_fma_mix_f32 v72, v28, v56, v72 op_sel_hi:[0,1,0]
	v_fma_mix_f32 v71, v28, v57, v71 op_sel_hi:[0,1,0]
	v_fma_mix_f32 v70, v28, v58, v70 op_sel_hi:[0,1,0]
	v_fma_mix_f32 v69, v28, v59, v69 op_sel_hi:[0,1,0]
	v_fma_mix_f32 v4, v28, v60, v4 op_sel_hi:[0,1,0]
	v_fma_mix_f32 v85, v29, v43, v85 op_sel_hi:[0,1,0]
	v_fma_mix_f32 v86, v29, v44, v86 op_sel_hi:[0,1,0]
	v_fma_mix_f32 v84, v29, v45, v84 op_sel_hi:[0,1,0]
	v_fma_mix_f32 v83, v29, v46, v83 op_sel_hi:[0,1,0]
	v_fma_mix_f32 v82, v29, v47, v82 op_sel_hi:[0,1,0]
	v_fma_mix_f32 v81, v29, v48, v81 op_sel_hi:[0,1,0]
	v_fma_mix_f32 v80, v29, v49, v80 op_sel_hi:[0,1,0]
	v_fma_mix_f32 v79, v29, v50, v79 op_sel_hi:[0,1,0]
	v_fma_mix_f32 v78, v29, v51, v78 op_sel_hi:[0,1,0]
	v_fma_mix_f32 v77, v29, v52, v77 op_sel_hi:[0,1,0]
	v_fma_mix_f32 v76, v29, v53, v76 op_sel_hi:[0,1,0]
	v_fma_mix_f32 v75, v29, v54, v75 op_sel_hi:[0,1,0]
	v_fma_mix_f32 v74, v29, v55, v74 op_sel_hi:[0,1,0]
	v_fma_mix_f32 v73, v29, v56, v73 op_sel_hi:[0,1,0]
	v_fma_mix_f32 v72, v29, v57, v72 op_sel_hi:[0,1,0]
	v_fma_mix_f32 v71, v29, v58, v71 op_sel_hi:[0,1,0]
	v_fma_mix_f32 v70, v29, v59, v70 op_sel_hi:[0,1,0]
	v_fma_mix_f32 v69, v29, v60, v69 op_sel_hi:[0,1,0]
	v_fma_mix_f32 v4, v29, v61, v4 op_sel_hi:[0,1,0]
	v_fma_mix_f32 v85, v30, v44, v85 op_sel_hi:[0,1,0]
	v_fma_mix_f32 v86, v30, v45, v86 op_sel_hi:[0,1,0]
	v_fma_mix_f32 v84, v30, v46, v84 op_sel_hi:[0,1,0]
	v_fma_mix_f32 v83, v30, v47, v83 op_sel_hi:[0,1,0]
	v_fma_mix_f32 v82, v30, v48, v82 op_sel_hi:[0,1,0]
	v_fma_mix_f32 v81, v30, v49, v81 op_sel_hi:[0,1,0]
	v_fma_mix_f32 v80, v30, v50, v80 op_sel_hi:[0,1,0]
	v_fma_mix_f32 v79, v30, v51, v79 op_sel_hi:[0,1,0]
	v_fma_mix_f32 v78, v30, v52, v78 op_sel_hi:[0,1,0]
	v_fma_mix_f32 v77, v30, v53, v77 op_sel_hi:[0,1,0]
	v_fma_mix_f32 v76, v30, v54, v76 op_sel_hi:[0,1,0]
	v_fma_mix_f32 v75, v30, v55, v75 op_sel_hi:[0,1,0]
	v_fma_mix_f32 v74, v30, v56, v74 op_sel_hi:[0,1,0]
	v_fma_mix_f32 v73, v30, v57, v73 op_sel_hi:[0,1,0]
	v_fma_mix_f32 v72, v30, v58, v72 op_sel_hi:[0,1,0]
	v_fma_mix_f32 v71, v30, v59, v71 op_sel_hi:[0,1,0]
	v_fma_mix_f32 v70, v30, v60, v70 op_sel_hi:[0,1,0]
	v_fma_mix_f32 v69, v30, v61, v69 op_sel_hi:[0,1,0]
	s_waitcnt lgkmcnt(13)
	v_fma_mix_f32 v4, v30, v62, v4 op_sel_hi:[0,1,0]
	v_fma_mix_f32 v85, v31, v45, v85 op_sel_hi:[0,1,0]
	v_fma_mix_f32 v86, v31, v46, v86 op_sel_hi:[0,1,0]
	v_fma_mix_f32 v84, v31, v47, v84 op_sel_hi:[0,1,0]
	v_fma_mix_f32 v83, v31, v48, v83 op_sel_hi:[0,1,0]
	v_fma_mix_f32 v82, v31, v49, v82 op_sel_hi:[0,1,0]
	v_fma_mix_f32 v81, v31, v50, v81 op_sel_hi:[0,1,0]
	v_fma_mix_f32 v80, v31, v51, v80 op_sel_hi:[0,1,0]
	v_fma_mix_f32 v79, v31, v52, v79 op_sel_hi:[0,1,0]
	v_fma_mix_f32 v78, v31, v53, v78 op_sel_hi:[0,1,0]
	v_fma_mix_f32 v77, v31, v54, v77 op_sel_hi:[0,1,0]
	v_fma_mix_f32 v76, v31, v55, v76 op_sel_hi:[0,1,0]
	v_fma_mix_f32 v75, v31, v56, v75 op_sel_hi:[0,1,0]
	v_fma_mix_f32 v74, v31, v57, v74 op_sel_hi:[0,1,0]
	v_fma_mix_f32 v73, v31, v58, v73 op_sel_hi:[0,1,0]
	v_fma_mix_f32 v72, v31, v59, v72 op_sel_hi:[0,1,0]
	v_fma_mix_f32 v71, v31, v60, v71 op_sel_hi:[0,1,0]
	v_fma_mix_f32 v70, v31, v61, v70 op_sel_hi:[0,1,0]
	v_fma_mix_f32 v69, v31, v62, v69 op_sel_hi:[0,1,0]
	s_waitcnt lgkmcnt(12)
	v_fma_mix_f32 v4, v31, v63, v4 op_sel_hi:[0,1,0]
	v_fma_mix_f32 v85, v32, v46, v85 op_sel_hi:[0,1,0]
	v_fma_mix_f32 v86, v32, v47, v86 op_sel_hi:[0,1,0]
	v_fma_mix_f32 v84, v32, v48, v84 op_sel_hi:[0,1,0]
	v_fma_mix_f32 v83, v32, v49, v83 op_sel_hi:[0,1,0]
	v_fma_mix_f32 v82, v32, v50, v82 op_sel_hi:[0,1,0]
	v_fma_mix_f32 v81, v32, v51, v81 op_sel_hi:[0,1,0]
	v_fma_mix_f32 v80, v32, v52, v80 op_sel_hi:[0,1,0]
	v_fma_mix_f32 v79, v32, v53, v79 op_sel_hi:[0,1,0]
	v_fma_mix_f32 v78, v32, v54, v78 op_sel_hi:[0,1,0]
	v_fma_mix_f32 v77, v32, v55, v77 op_sel_hi:[0,1,0]
	v_fma_mix_f32 v76, v32, v56, v76 op_sel_hi:[0,1,0]
	v_fma_mix_f32 v75, v32, v57, v75 op_sel_hi:[0,1,0]
	v_fma_mix_f32 v74, v32, v58, v74 op_sel_hi:[0,1,0]
	v_fma_mix_f32 v73, v32, v59, v73 op_sel_hi:[0,1,0]
	v_fma_mix_f32 v72, v32, v60, v72 op_sel_hi:[0,1,0]
	v_fma_mix_f32 v71, v32, v61, v71 op_sel_hi:[0,1,0]
	v_fma_mix_f32 v70, v32, v62, v70 op_sel_hi:[0,1,0]
	v_fma_mix_f32 v69, v32, v63, v69 op_sel_hi:[0,1,0]
	s_waitcnt lgkmcnt(11)
	v_fma_mix_f32 v4, v32, v64, v4 op_sel_hi:[0,1,0]
	v_fma_mix_f32 v85, v33, v47, v85 op_sel_hi:[0,1,0]
	v_fma_mix_f32 v86, v33, v48, v86 op_sel_hi:[0,1,0]
	v_fma_mix_f32 v84, v33, v49, v84 op_sel_hi:[0,1,0]
	v_fma_mix_f32 v83, v33, v50, v83 op_sel_hi:[0,1,0]
	v_fma_mix_f32 v82, v33, v51, v82 op_sel_hi:[0,1,0]
	v_fma_mix_f32 v81, v33, v52, v81 op_sel_hi:[0,1,0]
	v_fma_mix_f32 v80, v33, v53, v80 op_sel_hi:[0,1,0]
	v_fma_mix_f32 v79, v33, v54, v79 op_sel_hi:[0,1,0]
	v_fma_mix_f32 v78, v33, v55, v78 op_sel_hi:[0,1,0]
	v_fma_mix_f32 v77, v33, v56, v77 op_sel_hi:[0,1,0]
	v_fma_mix_f32 v76, v33, v57, v76 op_sel_hi:[0,1,0]
	v_fma_mix_f32 v75, v33, v58, v75 op_sel_hi:[0,1,0]
	v_fma_mix_f32 v74, v33, v59, v74 op_sel_hi:[0,1,0]
	v_fma_mix_f32 v73, v33, v60, v73 op_sel_hi:[0,1,0]
	v_fma_mix_f32 v72, v33, v61, v72 op_sel_hi:[0,1,0]
	v_fma_mix_f32 v71, v33, v62, v71 op_sel_hi:[0,1,0]
	v_fma_mix_f32 v70, v33, v63, v70 op_sel_hi:[0,1,0]
	v_fma_mix_f32 v69, v33, v64, v69 op_sel_hi:[0,1,0]
	s_waitcnt lgkmcnt(10)
	v_fma_mix_f32 v4, v33, v65, v4 op_sel_hi:[0,1,0]
	v_fma_mix_f32 v85, v34, v48, v85 op_sel_hi:[0,1,0]
	v_fma_mix_f32 v86, v34, v49, v86 op_sel_hi:[0,1,0]
	v_fma_mix_f32 v84, v34, v50, v84 op_sel_hi:[0,1,0]
	v_fma_mix_f32 v83, v34, v51, v83 op_sel_hi:[0,1,0]
	v_fma_mix_f32 v82, v34, v52, v82 op_sel_hi:[0,1,0]
	v_fma_mix_f32 v81, v34, v53, v81 op_sel_hi:[0,1,0]
	v_fma_mix_f32 v80, v34, v54, v80 op_sel_hi:[0,1,0]
	v_fma_mix_f32 v79, v34, v55, v79 op_sel_hi:[0,1,0]
	v_fma_mix_f32 v78, v34, v56, v78 op_sel_hi:[0,1,0]
	v_fma_mix_f32 v77, v34, v57, v77 op_sel_hi:[0,1,0]
	v_fma_mix_f32 v76, v34, v58, v76 op_sel_hi:[0,1,0]
	v_fma_mix_f32 v75, v34, v59, v75 op_sel_hi:[0,1,0]
	v_fma_mix_f32 v74, v34, v60, v74 op_sel_hi:[0,1,0]
	v_fma_mix_f32 v73, v34, v61, v73 op_sel_hi:[0,1,0]
	v_fma_mix_f32 v72, v34, v62, v72 op_sel_hi:[0,1,0]
	v_fma_mix_f32 v71, v34, v63, v71 op_sel_hi:[0,1,0]
	v_fma_mix_f32 v70, v34, v64, v70 op_sel_hi:[0,1,0]
	v_fma_mix_f32 v69, v34, v65, v69 op_sel_hi:[0,1,0]
	s_waitcnt lgkmcnt(9)
	v_fma_mix_f32 v4, v34, v66, v4 op_sel_hi:[0,1,0]
	v_fma_mix_f32 v85, v35, v49, v85 op_sel_hi:[0,1,0]
	v_fma_mix_f32 v86, v35, v50, v86 op_sel_hi:[0,1,0]
	v_fma_mix_f32 v84, v35, v51, v84 op_sel_hi:[0,1,0]
	v_fma_mix_f32 v83, v35, v52, v83 op_sel_hi:[0,1,0]
	v_fma_mix_f32 v82, v35, v53, v82 op_sel_hi:[0,1,0]
	v_fma_mix_f32 v81, v35, v54, v81 op_sel_hi:[0,1,0]
	v_fma_mix_f32 v80, v35, v55, v80 op_sel_hi:[0,1,0]
	v_fma_mix_f32 v79, v35, v56, v79 op_sel_hi:[0,1,0]
	v_fma_mix_f32 v78, v35, v57, v78 op_sel_hi:[0,1,0]
	v_fma_mix_f32 v77, v35, v58, v77 op_sel_hi:[0,1,0]
	v_fma_mix_f32 v76, v35, v59, v76 op_sel_hi:[0,1,0]
	v_fma_mix_f32 v75, v35, v60, v75 op_sel_hi:[0,1,0]
	v_fma_mix_f32 v74, v35, v61, v74 op_sel_hi:[0,1,0]
	v_fma_mix_f32 v73, v35, v62, v73 op_sel_hi:[0,1,0]
	v_fma_mix_f32 v72, v35, v63, v72 op_sel_hi:[0,1,0]
	v_fma_mix_f32 v71, v35, v64, v71 op_sel_hi:[0,1,0]
	v_fma_mix_f32 v70, v35, v65, v70 op_sel_hi:[0,1,0]
	v_fma_mix_f32 v69, v35, v66, v69 op_sel_hi:[0,1,0]
	s_waitcnt lgkmcnt(8)
	v_fma_mix_f32 v4, v35, v67, v4 op_sel_hi:[0,1,0]
	v_fma_mix_f32 v85, v36, v50, v85 op_sel_hi:[0,1,0]
	v_fma_mix_f32 v86, v36, v51, v86 op_sel_hi:[0,1,0]
	v_fma_mix_f32 v84, v36, v52, v84 op_sel_hi:[0,1,0]
	v_fma_mix_f32 v83, v36, v53, v83 op_sel_hi:[0,1,0]
	v_fma_mix_f32 v82, v36, v54, v82 op_sel_hi:[0,1,0]
	v_fma_mix_f32 v81, v36, v55, v81 op_sel_hi:[0,1,0]
	v_fma_mix_f32 v80, v36, v56, v80 op_sel_hi:[0,1,0]
	v_fma_mix_f32 v79, v36, v57, v79 op_sel_hi:[0,1,0]
	v_fma_mix_f32 v78, v36, v58, v78 op_sel_hi:[0,1,0]
	v_fma_mix_f32 v77, v36, v59, v77 op_sel_hi:[0,1,0]
	v_fma_mix_f32 v76, v36, v60, v76 op_sel_hi:[0,1,0]
	v_fma_mix_f32 v75, v36, v61, v75 op_sel_hi:[0,1,0]
	v_fma_mix_f32 v74, v36, v62, v74 op_sel_hi:[0,1,0]
	v_fma_mix_f32 v73, v36, v63, v73 op_sel_hi:[0,1,0]
	v_fma_mix_f32 v72, v36, v64, v72 op_sel_hi:[0,1,0]
	v_fma_mix_f32 v71, v36, v65, v71 op_sel_hi:[0,1,0]
	v_fma_mix_f32 v70, v36, v66, v70 op_sel_hi:[0,1,0]
	v_fma_mix_f32 v69, v36, v67, v69 op_sel_hi:[0,1,0]
	s_waitcnt lgkmcnt(7)
	v_fma_mix_f32 v4, v36, v68, v4 op_sel_hi:[0,1,0]
	ds_write2st64_b32 v8, v85, v86 offset0:104 offset1:112
	ds_write2st64_b32 v8, v84, v83 offset0:120 offset1:128
	ds_write2st64_b32 v8, v82, v81 offset0:136 offset1:144
	ds_write2st64_b32 v8, v80, v79 offset0:152 offset1:160
	ds_write2st64_b32 v8, v78, v77 offset0:168 offset1:176
	ds_write2st64_b32 v8, v76, v75 offset0:184 offset1:192
	ds_write2st64_b32 v8, v74, v73 offset0:200 offset1:208
	ds_write2st64_b32 v8, v72, v71 offset0:216 offset1:224
	ds_write2st64_b32 v8, v70, v69 offset0:232 offset1:240
	ds_write_b32 v8, v4 offset:63488
	s_waitcnt lgkmcnt(0)
	s_barrier
	s_and_saveexec_b64 s[4:5], vcc
	s_cbranch_execz .LBB0_35
	v_lshlrev_b32_e32 v16, 2, v20
	global_load_dwordx4 v[4:7], v16, s[12:13] offset:16
	global_load_dwordx4 v[8:11], v16, s[12:13]
	global_load_dwordx4 v[12:15], v16, s[14:15] offset:16
	s_nop 0
	global_load_dwordx4 v[16:19], v16, s[14:15]
	v_lshlrev_b32_e32 v20, 1, v20
	v_mov_b32_e32 v21, v2
	v_lshl_add_u64 v[24:25], s[22:23], 0, v[20:21]
	v_and_b32_e32 v20, 64, v235
	v_add_u32_e32 v20, 64, v20
	v_xor_b32_e32 v21, 32, v235
	v_cmp_lt_i32_e32 vcc, v21, v20
	v_lshlrev_b32_e32 v1, 5, v1
	v_lshl_or_b32 v1, v3, 11, v1
	v_cndmask_b32_e32 v21, v235, v21, vcc
	v_lshlrev_b32_e32 v28, 2, v21
	v_xor_b32_e32 v21, 16, v235
	v_cmp_lt_i32_e32 vcc, v21, v20
	v_add_u32_e32 v34, -8, v3
	s_mov_b64 s[26:27], 0
	v_cndmask_b32_e32 v21, v235, v21, vcc
	v_lshlrev_b32_e32 v29, 2, v21
	v_xor_b32_e32 v21, 8, v235
	v_cmp_lt_i32_e32 vcc, v21, v20
	s_nop 1
	v_cndmask_b32_e32 v21, v235, v21, vcc
	v_lshlrev_b32_e32 v30, 2, v21
	v_xor_b32_e32 v21, 4, v235
	v_cmp_lt_i32_e32 vcc, v21, v20
	s_nop 1
	v_cndmask_b32_e32 v21, v235, v21, vcc
	v_lshlrev_b32_e32 v31, 2, v21
	v_xor_b32_e32 v21, 2, v235
	v_cmp_lt_i32_e32 vcc, v21, v20
	s_nop 1
	v_cndmask_b32_e32 v21, v235, v21, vcc
	v_lshlrev_b32_e32 v32, 2, v21
	v_xor_b32_e32 v21, 1, v235
	v_cmp_lt_i32_e32 vcc, v21, v20
	s_nop 1
	v_cndmask_b32_e32 v20, v235, v21, vcc
	v_lshlrev_b32_e32 v33, 2, v20
	v_add_u32_e32 v20, s7, v3
	v_mul_lo_u32 v20, s25, v20
	s_add_i32 s7, 0, 0xf800
	v_add_u32_e32 v26, s6, v20
	s_lshl_b32 s6, s25, 3
	v_add_u32_e32 v1, s7, v1
	s_waitcnt vmcnt(0)
